# also: qkv V-tile epilogue with in-register 4x4 quad transposes (8-byte Vt stores instead of 2-byte), and XCD-aware tile assignment in the first round of the four output projections (8 M-tiles x 4 N-ti
# speedup vs baseline: 1.0422x; 1.0081x over previous
.LBB0_1328:
	s_and_b32 vcc_lo, s21, 7
	s_lshl_b32 vcc_lo, vcc_lo, 5
	s_lshr_b32 vcc_hi, s21, 3
	s_or_b32 vcc_lo, vcc_lo, vcc_hi
	s_cmpk_lt_i32 s21, 0x100
	s_cselect_b32 vcc_lo, vcc_lo, s21
	s_cmpk_lt_i32 s21, 0x100
	s_cselect_b64 s[10:11], -1, 0
	s_lshl_b32 s1, vcc_lo, 8
	s_and_b32 s12, s1, 0x300
	s_lshl_b32 s1, s21, 4
	s_lshl_b32 s0, vcc_lo, 6
	s_andn2_b32 s1, s1, 63
	s_and_b32 s0, s0, 0xffffff00
	s_addk_i32 s1, 0xf000
	s_cmpk_gt_i32 s21, 0xff
	s_cselect_b32 s22, 0x4000, s0
	s_cselect_b32 s0, s1, 0
	s_cselect_b32 s13, 2, 32
	s_cselect_b32 s8, 64, 0x80
	s_ashr_i32 s1, s0, 31
	s_lshl_b64 s[0:1], s[0:1], 1
	s_add_u32 s24, s88, s0
	s_waitcnt vmcnt(1)
	v_mov_b32_e32 v10, v174
	s_addc_u32 s25, s89, s1
	s_add_u32 s0, s28, s0
	v_readfirstlane_b32 s15, v10
	s_addc_u32 s1, s29, s1
	s_ashr_i32 s23, s15, 6
	v_bfe_u32 v0, v10, 2, 4
	s_lshl_b32 s26, s23, 4
	v_or_b32_e32 v2, s22, v0
	s_add_i32 s27, s26, 0x80
	v_or_b32_e32 v0, s12, v0
	s_and_b32 s14, s23, 3
	v_add_u32_e32 v12, s26, v2
	v_add_u32_e32 v4, s27, v2
	v_mov_b64_e32 v[2:3], s[24:25]
	s_waitcnt vmcnt(0)
	v_add_u32_e32 v8, s26, v0
	v_mov_b64_e32 v[6:7], s[0:1]
	v_add_u32_e32 v0, s27, v0
	s_ashr_i32 s15, s15, 8
	v_bfe_u32 v166, v10, 4, 2
	v_mad_i64_i32 v[4:5], s[24:25], v4, s16, v[2:3]
	v_mad_i64_i32 v[8:9], s[0:1], v8, s16, v[6:7]
	v_mad_i64_i32 v[6:7], s[0:1], v0, s16, v[6:7]
	v_mad_i64_i32 v[2:3], s[0:1], v12, s16, v[2:3]
	s_cmp_lg_u32 s15, 1
	v_bitop3_b32 v11, v166, v10, 3 bitop3:0x78
	s_cselect_b64 s[0:1], -1, 0
	s_lshl_b32 s24, s23, 10
	v_lshlrev_b32_e32 v0, 4, v11
	s_add_i32 s23, s24, 0
	v_lshl_add_u64 v[158:159], v[2:3], 0, v[0:1]
	s_mov_b32 m0, s23
	v_lshl_add_u64 v[160:161], v[4:5], 0, v[0:1]
	global_load_lds_dwordx4 v[158:159], off
	s_add_i32 m0, s23, 0x2000
	v_lshl_add_u64 v[162:163], v[8:9], 0, v[0:1]
	global_load_lds_dwordx4 v[160:161], off
	s_add_i32 m0, s23, 0x4000
	v_lshl_add_u64 v[164:165], v[6:7], 0, v[0:1]
	global_load_lds_dwordx4 v[162:163], off
	s_add_i32 m0, s23, 0x6000
	v_lshl_add_u64 v[2:3], v[158:159], 0, 64
	global_load_lds_dwordx4 v[164:165], off
	s_add_i32 m0, s23, 0x8000
	s_add_i32 s25, s24, 0x2000
	global_load_lds_dwordx4 v[2:3], off
	v_lshl_add_u64 v[2:3], v[160:161], 0, 64
	s_add_i32 m0, s23, 0xa000
	v_lshrrev_b32_e32 v0, 2, v10
	global_load_lds_dwordx4 v[2:3], off
	v_lshl_add_u64 v[2:3], v[162:163], 0, 64
	s_add_i32 m0, s23, 0xc000
	v_bitop3_b32 v0, v166, v0, 3 bitop3:0x78
	global_load_lds_dwordx4 v[2:3], off
	v_lshl_add_u64 v[2:3], v[164:165], 0, 64
	s_add_i32 m0, s23, 0xe000
	s_or_b64 s[0:1], s[10:11], s[0:1]
	global_load_lds_dwordx4 v[2:3], off
	v_lshl_add_u64 v[2:3], v[158:159], 0, s[8:9]
	s_add_i32 m0, s18, s24
	v_and_b32_e32 v167, 15, v10
	global_load_lds_dwordx4 v[2:3], off
	v_lshl_add_u64 v[2:3], v[160:161], 0, s[8:9]
	s_add_i32 m0, s18, s25
	v_lshlrev_b32_e32 v169, 4, v0
	global_load_lds_dwordx4 v[2:3], off
	v_lshl_add_u64 v[2:3], v[162:163], 0, s[8:9]
	s_add_i32 m0, s19, s24
	v_mov_b32_e32 v0, v1
	global_load_lds_dwordx4 v[2:3], off
	v_lshl_add_u64 v[2:3], v[164:165], 0, s[8:9]
	s_add_i32 m0, s19, s25
	v_cndmask_b32_e64 v4, 0, 1, s[0:1]
	global_load_lds_dwordx4 v[2:3], off
	s_waitcnt vmcnt(8)
	v_mov_b32_e32 v2, v1
	v_mov_b32_e32 v3, v1
	s_waitcnt lgkmcnt(0)
	s_barrier
	v_mov_b64_e32 v[20:21], v[2:3]
	v_mov_b64_e32 v[24:25], v[2:3]
	v_mov_b64_e32 v[28:29], v[2:3]
	v_mov_b64_e32 v[32:33], v[2:3]
	v_mov_b64_e32 v[36:37], v[2:3]
	v_mov_b64_e32 v[40:41], v[2:3]
	v_mov_b64_e32 v[44:45], v[2:3]
	s_waitcnt vmcnt(0)
	v_mov_b64_e32 v[48:49], v[2:3]
	v_mov_b64_e32 v[52:53], v[2:3]
	v_mov_b64_e32 v[56:57], v[2:3]
	v_mov_b64_e32 v[60:61], v[2:3]
	v_mov_b64_e32 v[64:65], v[2:3]
	v_mov_b64_e32 v[68:69], v[2:3]
	v_mov_b64_e32 v[72:73], v[2:3]
	v_mov_b64_e32 v[76:77], v[2:3]
	v_mov_b64_e32 v[80:81], v[2:3]
	v_mov_b64_e32 v[84:85], v[2:3]
	v_mov_b64_e32 v[88:89], v[2:3]
	v_mov_b64_e32 v[92:93], v[2:3]
	v_mov_b64_e32 v[96:97], v[2:3]
	v_mov_b64_e32 v[100:101], v[2:3]
	v_mov_b64_e32 v[104:105], v[2:3]
	v_mov_b64_e32 v[108:109], v[2:3]
	v_mov_b64_e32 v[112:113], v[2:3]
	v_mov_b64_e32 v[116:117], v[2:3]
	v_mov_b64_e32 v[120:121], v[2:3]
	v_mov_b64_e32 v[124:125], v[2:3]
	v_mov_b64_e32 v[128:129], v[2:3]
	v_mov_b64_e32 v[16:17], v[2:3]
	v_mov_b64_e32 v[12:13], v[2:3]
	v_mov_b64_e32 v[8:9], v[2:3]
	v_cmp_ne_u32_e64 s[0:1], 1, v4
	v_mov_b64_e32 v[18:19], v[0:1]
	v_mov_b64_e32 v[22:23], v[0:1]
	v_mov_b64_e32 v[26:27], v[0:1]
	v_mov_b64_e32 v[30:31], v[0:1]
	v_mov_b64_e32 v[34:35], v[0:1]
	v_mov_b64_e32 v[38:39], v[0:1]
	v_mov_b64_e32 v[42:43], v[0:1]
	v_mov_b64_e32 v[46:47], v[0:1]
	v_mov_b64_e32 v[50:51], v[0:1]
	v_mov_b64_e32 v[54:55], v[0:1]
	v_mov_b64_e32 v[58:59], v[0:1]
	v_mov_b64_e32 v[62:63], v[0:1]
	v_mov_b64_e32 v[66:67], v[0:1]
	v_mov_b64_e32 v[70:71], v[0:1]
	v_mov_b64_e32 v[74:75], v[0:1]
	v_mov_b64_e32 v[78:79], v[0:1]
	v_mov_b64_e32 v[82:83], v[0:1]
	v_mov_b64_e32 v[86:87], v[0:1]
	v_mov_b64_e32 v[90:91], v[0:1]
	v_mov_b64_e32 v[94:95], v[0:1]
	v_mov_b64_e32 v[98:99], v[0:1]
	v_mov_b64_e32 v[102:103], v[0:1]
	v_mov_b64_e32 v[106:107], v[0:1]
	v_mov_b64_e32 v[110:111], v[0:1]
	v_mov_b64_e32 v[114:115], v[0:1]
	v_mov_b64_e32 v[118:119], v[0:1]
	v_mov_b64_e32 v[122:123], v[0:1]
	v_mov_b64_e32 v[126:127], v[0:1]
	v_mov_b64_e32 v[14:15], v[0:1]
	v_mov_b64_e32 v[10:11], v[0:1]
	v_mov_b64_e32 v[6:7], v[0:1]
	v_mov_b64_e32 v[4:5], v[2:3]
	s_add_i32 s24, s13, -1
	s_lshl_b32 s25, s14, 12
	v_lshlrev_b32_e32 v168, 6, v167
	s_lshl_b32 s26, s15, 13
	s_mov_b32 s27, 0x18000
	v_mov_b64_e32 v[2:3], v[0:1]
	s_mov_b32 s34, s9
	s_branch .LBB0_1330

.LBB0_1661:
	s_and_b32 vcc_lo, s21, 7
	s_lshl_b32 vcc_lo, vcc_lo, 5
	s_lshr_b32 vcc_hi, s21, 3
	s_or_b32 vcc_lo, vcc_lo, vcc_hi
	s_cmpk_lt_i32 s21, 0x100
	s_cselect_b32 vcc_lo, vcc_lo, s21
	s_cmpk_lt_i32 s21, 0x100
	s_cselect_b64 s[10:11], -1, 0
	s_lshl_b32 s0, vcc_lo, 6
	s_and_b32 s0, s0, 0xffffff00
	s_lshl_b32 s1, vcc_lo, 8
	s_and_b32 s12, s1, 0x300
	s_add_i32 s1, s0, 0xffffc000
	s_cmpk_gt_i32 s21, 0xff
	s_cselect_b32 s22, 0x4000, s0
	s_cselect_b32 s0, s1, 0
	s_cselect_b32 s13, 8, 0x80
	s_ashr_i32 s1, s0, 31
	s_lshl_b64 s[0:1], s[0:1], 1
	s_add_u32 s24, s96, s0
	s_addc_u32 s25, s97, s1
	s_waitcnt vmcnt(1)
	v_mov_b32_e32 v10, v174
	s_add_u32 s0, s92, s0
	s_addc_u32 s1, s93, s1
	v_readfirstlane_b32 s6, v10
	s_ashr_i32 s23, s6, 6
	v_bfe_u32 v0, v10, 2, 4
	s_lshl_b32 s15, s23, 4
	v_or_b32_e32 v2, s22, v0
	s_add_i32 s26, s15, 0x80
	v_or_b32_e32 v0, s12, v0
	s_and_b32 s14, s23, 3
	v_add_u32_e32 v12, s15, v2
	v_add_u32_e32 v4, s26, v2
	v_mov_b64_e32 v[2:3], s[24:25]
	s_waitcnt vmcnt(0)
	v_add_u32_e32 v8, s15, v0
	v_mov_b64_e32 v[6:7], s[0:1]
	v_add_u32_e32 v0, s26, v0
	s_ashr_i32 s15, s6, 8
	v_bfe_u32 v166, v10, 4, 2
	v_mad_i64_i32 v[4:5], s[24:25], v4, s16, v[2:3]
	v_mad_i64_i32 v[8:9], s[0:1], v8, s16, v[6:7]
	v_mad_i64_i32 v[6:7], s[0:1], v0, s16, v[6:7]
	v_mad_i64_i32 v[2:3], s[0:1], v12, s16, v[2:3]
	s_cmp_lg_u32 s15, 1
	v_bitop3_b32 v11, v166, v10, 3 bitop3:0x78
	s_cselect_b64 s[0:1], -1, 0
	s_lshl_b32 s6, s23, 10
	v_lshlrev_b32_e32 v0, 4, v11
	s_add_i32 s23, s6, 0
	v_lshl_add_u64 v[158:159], v[2:3], 0, v[0:1]
	s_mov_b32 m0, s23
	v_lshl_add_u64 v[160:161], v[4:5], 0, v[0:1]
	global_load_lds_dwordx4 v[158:159], off
	s_add_i32 m0, s23, 0x2000
	v_lshl_add_u64 v[162:163], v[8:9], 0, v[0:1]
	global_load_lds_dwordx4 v[160:161], off
	s_add_i32 m0, s23, 0x4000
	v_lshl_add_u64 v[164:165], v[6:7], 0, v[0:1]
	global_load_lds_dwordx4 v[162:163], off
	s_add_i32 m0, s23, 0x6000
	v_lshl_add_u64 v[2:3], v[158:159], 0, 64
	global_load_lds_dwordx4 v[164:165], off
	s_add_i32 m0, s23, 0x8000
	s_add_i32 s24, s6, 0x2000
	global_load_lds_dwordx4 v[2:3], off
	v_lshl_add_u64 v[2:3], v[160:161], 0, 64
	s_add_i32 m0, s23, 0xa000
	v_lshrrev_b32_e32 v0, 2, v10
	global_load_lds_dwordx4 v[2:3], off
	v_lshl_add_u64 v[2:3], v[162:163], 0, 64
	s_add_i32 m0, s23, 0xc000
	v_bitop3_b32 v0, v166, v0, 3 bitop3:0x78
	global_load_lds_dwordx4 v[2:3], off
	v_lshl_add_u64 v[2:3], v[164:165], 0, 64
	s_add_i32 m0, s23, 0xe000
	s_or_b64 s[0:1], s[10:11], s[0:1]
	global_load_lds_dwordx4 v[2:3], off
	v_lshl_add_u64 v[2:3], v[158:159], 0, s[8:9]
	s_add_i32 m0, s18, s6
	v_and_b32_e32 v167, 15, v10
	global_load_lds_dwordx4 v[2:3], off
	v_lshl_add_u64 v[2:3], v[160:161], 0, s[8:9]
	s_add_i32 m0, s18, s24
	v_lshlrev_b32_e32 v169, 4, v0
	global_load_lds_dwordx4 v[2:3], off
	v_lshl_add_u64 v[2:3], v[162:163], 0, s[8:9]
	s_add_i32 m0, s19, s6
	v_mov_b32_e32 v0, v1
	global_load_lds_dwordx4 v[2:3], off
	v_lshl_add_u64 v[2:3], v[164:165], 0, s[8:9]
	s_add_i32 m0, s19, s24
	v_cndmask_b32_e64 v4, 0, 1, s[0:1]
	global_load_lds_dwordx4 v[2:3], off
	s_waitcnt vmcnt(8)
	v_mov_b32_e32 v2, v1
	v_mov_b32_e32 v3, v1
	s_waitcnt lgkmcnt(0)
	s_barrier
	v_mov_b64_e32 v[20:21], v[2:3]
	v_mov_b64_e32 v[24:25], v[2:3]
	v_mov_b64_e32 v[28:29], v[2:3]
	v_mov_b64_e32 v[32:33], v[2:3]
	v_mov_b64_e32 v[36:37], v[2:3]
	v_mov_b64_e32 v[40:41], v[2:3]
	v_mov_b64_e32 v[44:45], v[2:3]
	v_mov_b64_e32 v[48:49], v[2:3]
	v_mov_b64_e32 v[52:53], v[2:3]
	v_mov_b64_e32 v[56:57], v[2:3]
	v_mov_b64_e32 v[60:61], v[2:3]
	v_mov_b64_e32 v[64:65], v[2:3]
	v_mov_b64_e32 v[68:69], v[2:3]
	v_mov_b64_e32 v[72:73], v[2:3]
	v_mov_b64_e32 v[76:77], v[2:3]
	v_mov_b64_e32 v[80:81], v[2:3]
	v_mov_b64_e32 v[84:85], v[2:3]
	v_mov_b64_e32 v[88:89], v[2:3]
	v_mov_b64_e32 v[92:93], v[2:3]
	v_mov_b64_e32 v[96:97], v[2:3]
	v_mov_b64_e32 v[100:101], v[2:3]
	v_mov_b64_e32 v[104:105], v[2:3]
	v_mov_b64_e32 v[108:109], v[2:3]
	v_mov_b64_e32 v[112:113], v[2:3]
	v_mov_b64_e32 v[116:117], v[2:3]
	v_mov_b64_e32 v[120:121], v[2:3]
	v_mov_b64_e32 v[124:125], v[2:3]
	v_mov_b64_e32 v[128:129], v[2:3]
	v_mov_b64_e32 v[16:17], v[2:3]
	v_mov_b64_e32 v[12:13], v[2:3]
	v_mov_b64_e32 v[8:9], v[2:3]
	v_cmp_ne_u32_e64 s[0:1], 1, v4
	v_mov_b64_e32 v[18:19], v[0:1]
	v_mov_b64_e32 v[22:23], v[0:1]
	v_mov_b64_e32 v[26:27], v[0:1]
	v_mov_b64_e32 v[30:31], v[0:1]
	v_mov_b64_e32 v[34:35], v[0:1]
	v_mov_b64_e32 v[38:39], v[0:1]
	v_mov_b64_e32 v[42:43], v[0:1]
	v_mov_b64_e32 v[46:47], v[0:1]
	v_mov_b64_e32 v[50:51], v[0:1]
	v_mov_b64_e32 v[54:55], v[0:1]
	v_mov_b64_e32 v[58:59], v[0:1]
	v_mov_b64_e32 v[62:63], v[0:1]
	v_mov_b64_e32 v[66:67], v[0:1]
	v_mov_b64_e32 v[70:71], v[0:1]
	v_mov_b64_e32 v[74:75], v[0:1]
	v_mov_b64_e32 v[78:79], v[0:1]
	v_mov_b64_e32 v[82:83], v[0:1]
	v_mov_b64_e32 v[86:87], v[0:1]
	v_mov_b64_e32 v[90:91], v[0:1]
	v_mov_b64_e32 v[94:95], v[0:1]
	v_mov_b64_e32 v[98:99], v[0:1]
	v_mov_b64_e32 v[102:103], v[0:1]
	v_mov_b64_e32 v[106:107], v[0:1]
	v_mov_b64_e32 v[110:111], v[0:1]
	v_mov_b64_e32 v[114:115], v[0:1]
	v_mov_b64_e32 v[118:119], v[0:1]
	v_mov_b64_e32 v[122:123], v[0:1]
	v_mov_b64_e32 v[126:127], v[0:1]
	v_mov_b64_e32 v[14:15], v[0:1]
	v_mov_b64_e32 v[10:11], v[0:1]
	v_mov_b64_e32 v[6:7], v[0:1]
	v_mov_b64_e32 v[4:5], v[2:3]
	s_add_i32 s24, s13, -1
	s_lshl_b32 s25, s14, 12
	v_lshlrev_b32_e32 v168, 6, v167
	s_lshl_b32 s26, s15, 13
	s_mov_b32 s27, 0x18000
	v_mov_b64_e32 v[2:3], v[0:1]
	s_mov_b32 s30, s7
	s_branch .LBB0_1663

.LBB0_1917:
	s_lshl_b32 s0, s6, 6
	s_or_b32 s8, s0, s4
	s_waitcnt lgkmcnt(0)
	v_lshl_or_b32 v130, v172, 2, s8
	v_readlane_b32 s64, v192, 0
	s_waitcnt vmcnt(0)
	v_ashrrev_i32_e32 v131, 31, v130
	v_readlane_b32 s68, v192, 4
	v_readlane_b32 s69, v192, 5
	s_waitcnt lgkmcnt(0)
	s_barrier
	s_cmpk_eq_i32 s4, 0x500
	s_cbranch_scc0 .Lqv_orig
	s_cmp_lt_u32 s62, 0x4000
	s_cbranch_scc0 .Lqv_orig
	s_and_b32 s7, s62, 0xf00
	s_cmpk_eq_i32 s7, 0xf00
	s_cselect_b32 s7, 1, 0
	s_and_b32 s7, s7, s5
	s_lshr_b32 s0, s62, 12
	s_lshl_b32 s0, s0, 7
	v_add_u32_e32 v248, s0, v176
	v_lshlrev_b32_e32 v248, 10, v248
	s_lshl_b32 s0, s6, 8
	s_add_u32 s0, s0, 0x7284000
	v_lshl_add_u32 v248, v172, 4, v248
	v_add_u32_e32 v248, s0, v248
	v_lshlrev_b32_e32 v246, 2, v130
	global_load_dwordx4 v[194:197], v246, s[68:69] offset:0
	global_load_dwordx4 v[198:201], v246, s[68:69] offset:64
	global_load_dwordx4 v[202:205], v246, s[68:69] offset:128
	global_load_dwordx4 v[206:209], v246, s[68:69] offset:192
	s_lshr_b32 s0, s62, 12
	s_lshl_b32 s0, s0, 2
	s_add_i32 s0, s0, s6
	s_lshl_b32 s0, s0, 6
	v_and_b32_e32 v246, 3, v176
	v_lshl_add_u32 v246, v172, 2, v246
	v_add_u32_e32 v246, s0, v246
	v_lshlrev_b32_e32 v246, 13, v246
	s_and_b32 s0, s62, 0xfff
	s_lshl_b32 s1, s5, 7
	s_add_i32 s0, s0, s1
	v_and_b32_e32 v247, 12, v176
	v_add_u32_e32 v247, s0, v247
	v_lshl_add_u32 v242, v247, 1, v246
	v_add_u32_e32 v243, 0x20000, v242
	v_add_u32_e32 v244, 0x40000, v242
	v_add_u32_e32 v245, 0x60000, v242
	s_add_u32 s0, s84, 0xa5408c0
	s_addc_u32 s1, s85, 0
	s_waitcnt vmcnt(0)
	v_add_f32_e32 v126, v126, v194
	v_add_f32_e32 v127, v127, v195
	v_add_f32_e32 v128, v128, v196
	v_add_f32_e32 v129, v129, v197
	v_add_f32_e32 v122, v122, v198
	v_add_f32_e32 v123, v123, v199
	v_add_f32_e32 v124, v124, v200
	v_add_f32_e32 v125, v125, v201
	v_add_f32_e32 v118, v118, v202
	v_add_f32_e32 v119, v119, v203
	v_add_f32_e32 v120, v120, v204
	v_add_f32_e32 v121, v121, v205
	v_add_f32_e32 v114, v114, v206
	v_add_f32_e32 v115, v115, v207
	v_add_f32_e32 v116, v116, v208
	v_add_f32_e32 v117, v117, v209
	s_cmp_lg_u32 s7, 0
	s_cbranch_scc0 .Lqv_nc0
	global_store_dwordx4 v248, v[126:129], s[82:83] offset:0
	global_store_dwordx4 v248, v[122:125], s[82:83] offset:64
	global_store_dwordx4 v248, v[118:121], s[82:83] offset:128
	global_store_dwordx4 v248, v[114:117], s[82:83] offset:192
	v_add_u32_e32 v248, 0x4000, v248
.Lqv_nc0:
	s_mov_b32 vcc_lo, 0x55555555
	s_mov_b32 vcc_hi, 0x55555555
	s_nop 1
	v_cndmask_b32_dpp v210, v127, v126, vcc quad_perm:[1,0,3,2] row_mask:0xf bank_mask:0xf
	v_cndmask_b32_dpp v212, v129, v128, vcc quad_perm:[1,0,3,2] row_mask:0xf bank_mask:0xf
	v_cndmask_b32_dpp v214, v123, v122, vcc quad_perm:[1,0,3,2] row_mask:0xf bank_mask:0xf
	v_cndmask_b32_dpp v216, v125, v124, vcc quad_perm:[1,0,3,2] row_mask:0xf bank_mask:0xf
	v_cndmask_b32_dpp v218, v119, v118, vcc quad_perm:[1,0,3,2] row_mask:0xf bank_mask:0xf
	v_cndmask_b32_dpp v220, v121, v120, vcc quad_perm:[1,0,3,2] row_mask:0xf bank_mask:0xf
	v_cndmask_b32_dpp v222, v115, v114, vcc quad_perm:[1,0,3,2] row_mask:0xf bank_mask:0xf
	v_cndmask_b32_dpp v224, v117, v116, vcc quad_perm:[1,0,3,2] row_mask:0xf bank_mask:0xf
	s_mov_b32 vcc_lo, 0xaaaaaaaa
	s_mov_b32 vcc_hi, 0xaaaaaaaa
	s_nop 1
	v_cndmask_b32_dpp v211, v126, v127, vcc quad_perm:[1,0,3,2] row_mask:0xf bank_mask:0xf
	v_cndmask_b32_dpp v213, v128, v129, vcc quad_perm:[1,0,3,2] row_mask:0xf bank_mask:0xf
	v_cndmask_b32_dpp v215, v122, v123, vcc quad_perm:[1,0,3,2] row_mask:0xf bank_mask:0xf
	v_cndmask_b32_dpp v217, v124, v125, vcc quad_perm:[1,0,3,2] row_mask:0xf bank_mask:0xf
	v_cndmask_b32_dpp v219, v118, v119, vcc quad_perm:[1,0,3,2] row_mask:0xf bank_mask:0xf
	v_cndmask_b32_dpp v221, v120, v121, vcc quad_perm:[1,0,3,2] row_mask:0xf bank_mask:0xf
	v_cndmask_b32_dpp v223, v114, v115, vcc quad_perm:[1,0,3,2] row_mask:0xf bank_mask:0xf
	v_cndmask_b32_dpp v225, v116, v117, vcc quad_perm:[1,0,3,2] row_mask:0xf bank_mask:0xf
	s_mov_b32 vcc_lo, 0x33333333
	s_mov_b32 vcc_hi, 0x33333333
	s_nop 1
	v_cndmask_b32_dpp v126, v212, v210, vcc quad_perm:[2,3,0,1] row_mask:0xf bank_mask:0xf
	v_cndmask_b32_dpp v127, v213, v211, vcc quad_perm:[2,3,0,1] row_mask:0xf bank_mask:0xf
	v_cndmask_b32_dpp v122, v216, v214, vcc quad_perm:[2,3,0,1] row_mask:0xf bank_mask:0xf
	v_cndmask_b32_dpp v123, v217, v215, vcc quad_perm:[2,3,0,1] row_mask:0xf bank_mask:0xf
	v_cndmask_b32_dpp v118, v220, v218, vcc quad_perm:[2,3,0,1] row_mask:0xf bank_mask:0xf
	v_cndmask_b32_dpp v119, v221, v219, vcc quad_perm:[2,3,0,1] row_mask:0xf bank_mask:0xf
	v_cndmask_b32_dpp v114, v224, v222, vcc quad_perm:[2,3,0,1] row_mask:0xf bank_mask:0xf
	v_cndmask_b32_dpp v115, v225, v223, vcc quad_perm:[2,3,0,1] row_mask:0xf bank_mask:0xf
	s_mov_b32 vcc_lo, 0xcccccccc
	s_mov_b32 vcc_hi, 0xcccccccc
	s_nop 1
	v_cndmask_b32_dpp v128, v210, v212, vcc quad_perm:[2,3,0,1] row_mask:0xf bank_mask:0xf
	v_cndmask_b32_dpp v129, v211, v213, vcc quad_perm:[2,3,0,1] row_mask:0xf bank_mask:0xf
	v_cndmask_b32_dpp v124, v214, v216, vcc quad_perm:[2,3,0,1] row_mask:0xf bank_mask:0xf
	v_cndmask_b32_dpp v125, v215, v217, vcc quad_perm:[2,3,0,1] row_mask:0xf bank_mask:0xf
	v_cndmask_b32_dpp v120, v218, v220, vcc quad_perm:[2,3,0,1] row_mask:0xf bank_mask:0xf
	v_cndmask_b32_dpp v121, v219, v221, vcc quad_perm:[2,3,0,1] row_mask:0xf bank_mask:0xf
	v_cndmask_b32_dpp v116, v222, v224, vcc quad_perm:[2,3,0,1] row_mask:0xf bank_mask:0xf
	v_cndmask_b32_dpp v117, v223, v225, vcc quad_perm:[2,3,0,1] row_mask:0xf bank_mask:0xf
	v_cvt_pk_bf16_f32 v226, v126, v127
	v_cvt_pk_bf16_f32 v227, v128, v129
	v_cvt_pk_bf16_f32 v228, v122, v123
	v_cvt_pk_bf16_f32 v229, v124, v125
	v_cvt_pk_bf16_f32 v230, v118, v119
	v_cvt_pk_bf16_f32 v231, v120, v121
	v_cvt_pk_bf16_f32 v232, v114, v115
	v_cvt_pk_bf16_f32 v233, v116, v117
	global_store_dwordx2 v242, v[226:227], s[0:1] offset:0
	global_store_dwordx2 v243, v[228:229], s[0:1] offset:0
	global_store_dwordx2 v244, v[230:231], s[0:1] offset:0
	global_store_dwordx2 v245, v[232:233], s[0:1] offset:0
	v_add_f32_e32 v110, v110, v194
	v_add_f32_e32 v111, v111, v195
	v_add_f32_e32 v112, v112, v196
	v_add_f32_e32 v113, v113, v197
	v_add_f32_e32 v106, v106, v198
	v_add_f32_e32 v107, v107, v199
	v_add_f32_e32 v108, v108, v200
	v_add_f32_e32 v109, v109, v201
	v_add_f32_e32 v102, v102, v202
	v_add_f32_e32 v103, v103, v203
	v_add_f32_e32 v104, v104, v204
	v_add_f32_e32 v105, v105, v205
	v_add_f32_e32 v98, v98, v206
	v_add_f32_e32 v99, v99, v207
	v_add_f32_e32 v100, v100, v208
	v_add_f32_e32 v101, v101, v209
	s_cmp_lg_u32 s7, 0
	s_cbranch_scc0 .Lqv_nc1
	global_store_dwordx4 v248, v[110:113], s[82:83] offset:0
	global_store_dwordx4 v248, v[106:109], s[82:83] offset:64
	global_store_dwordx4 v248, v[102:105], s[82:83] offset:128
	global_store_dwordx4 v248, v[98:101], s[82:83] offset:192
	v_add_u32_e32 v248, 0x4000, v248
.Lqv_nc1:
	s_mov_b32 vcc_lo, 0x55555555
	s_mov_b32 vcc_hi, 0x55555555
	s_nop 1
	v_cndmask_b32_dpp v210, v111, v110, vcc quad_perm:[1,0,3,2] row_mask:0xf bank_mask:0xf
	v_cndmask_b32_dpp v212, v113, v112, vcc quad_perm:[1,0,3,2] row_mask:0xf bank_mask:0xf
	v_cndmask_b32_dpp v214, v107, v106, vcc quad_perm:[1,0,3,2] row_mask:0xf bank_mask:0xf
	v_cndmask_b32_dpp v216, v109, v108, vcc quad_perm:[1,0,3,2] row_mask:0xf bank_mask:0xf
	v_cndmask_b32_dpp v218, v103, v102, vcc quad_perm:[1,0,3,2] row_mask:0xf bank_mask:0xf
	v_cndmask_b32_dpp v220, v105, v104, vcc quad_perm:[1,0,3,2] row_mask:0xf bank_mask:0xf
	v_cndmask_b32_dpp v222, v99, v98, vcc quad_perm:[1,0,3,2] row_mask:0xf bank_mask:0xf
	v_cndmask_b32_dpp v224, v101, v100, vcc quad_perm:[1,0,3,2] row_mask:0xf bank_mask:0xf
	s_mov_b32 vcc_lo, 0xaaaaaaaa
	s_mov_b32 vcc_hi, 0xaaaaaaaa
	s_nop 1
	v_cndmask_b32_dpp v211, v110, v111, vcc quad_perm:[1,0,3,2] row_mask:0xf bank_mask:0xf
	v_cndmask_b32_dpp v213, v112, v113, vcc quad_perm:[1,0,3,2] row_mask:0xf bank_mask:0xf
	v_cndmask_b32_dpp v215, v106, v107, vcc quad_perm:[1,0,3,2] row_mask:0xf bank_mask:0xf
	v_cndmask_b32_dpp v217, v108, v109, vcc quad_perm:[1,0,3,2] row_mask:0xf bank_mask:0xf
	v_cndmask_b32_dpp v219, v102, v103, vcc quad_perm:[1,0,3,2] row_mask:0xf bank_mask:0xf
	v_cndmask_b32_dpp v221, v104, v105, vcc quad_perm:[1,0,3,2] row_mask:0xf bank_mask:0xf
	v_cndmask_b32_dpp v223, v98, v99, vcc quad_perm:[1,0,3,2] row_mask:0xf bank_mask:0xf
	v_cndmask_b32_dpp v225, v100, v101, vcc quad_perm:[1,0,3,2] row_mask:0xf bank_mask:0xf
	s_mov_b32 vcc_lo, 0x33333333
	s_mov_b32 vcc_hi, 0x33333333
	s_nop 1
	v_cndmask_b32_dpp v110, v212, v210, vcc quad_perm:[2,3,0,1] row_mask:0xf bank_mask:0xf
	v_cndmask_b32_dpp v111, v213, v211, vcc quad_perm:[2,3,0,1] row_mask:0xf bank_mask:0xf
	v_cndmask_b32_dpp v106, v216, v214, vcc quad_perm:[2,3,0,1] row_mask:0xf bank_mask:0xf
	v_cndmask_b32_dpp v107, v217, v215, vcc quad_perm:[2,3,0,1] row_mask:0xf bank_mask:0xf
	v_cndmask_b32_dpp v102, v220, v218, vcc quad_perm:[2,3,0,1] row_mask:0xf bank_mask:0xf
	v_cndmask_b32_dpp v103, v221, v219, vcc quad_perm:[2,3,0,1] row_mask:0xf bank_mask:0xf
	v_cndmask_b32_dpp v98, v224, v222, vcc quad_perm:[2,3,0,1] row_mask:0xf bank_mask:0xf
	v_cndmask_b32_dpp v99, v225, v223, vcc quad_perm:[2,3,0,1] row_mask:0xf bank_mask:0xf
	s_mov_b32 vcc_lo, 0xcccccccc
	s_mov_b32 vcc_hi, 0xcccccccc
	s_nop 1
	v_cndmask_b32_dpp v112, v210, v212, vcc quad_perm:[2,3,0,1] row_mask:0xf bank_mask:0xf
	v_cndmask_b32_dpp v113, v211, v213, vcc quad_perm:[2,3,0,1] row_mask:0xf bank_mask:0xf
	v_cndmask_b32_dpp v108, v214, v216, vcc quad_perm:[2,3,0,1] row_mask:0xf bank_mask:0xf
	v_cndmask_b32_dpp v109, v215, v217, vcc quad_perm:[2,3,0,1] row_mask:0xf bank_mask:0xf
	v_cndmask_b32_dpp v104, v218, v220, vcc quad_perm:[2,3,0,1] row_mask:0xf bank_mask:0xf
	v_cndmask_b32_dpp v105, v219, v221, vcc quad_perm:[2,3,0,1] row_mask:0xf bank_mask:0xf
	v_cndmask_b32_dpp v100, v222, v224, vcc quad_perm:[2,3,0,1] row_mask:0xf bank_mask:0xf
	v_cndmask_b32_dpp v101, v223, v225, vcc quad_perm:[2,3,0,1] row_mask:0xf bank_mask:0xf
	v_cvt_pk_bf16_f32 v234, v110, v111
	v_cvt_pk_bf16_f32 v235, v112, v113
	v_cvt_pk_bf16_f32 v236, v106, v107
	v_cvt_pk_bf16_f32 v237, v108, v109
	v_cvt_pk_bf16_f32 v238, v102, v103
	v_cvt_pk_bf16_f32 v239, v104, v105
	v_cvt_pk_bf16_f32 v240, v98, v99
	v_cvt_pk_bf16_f32 v241, v100, v101
	global_store_dwordx2 v242, v[234:235], s[0:1] offset:32
	global_store_dwordx2 v243, v[236:237], s[0:1] offset:32
	global_store_dwordx2 v244, v[238:239], s[0:1] offset:32
	global_store_dwordx2 v245, v[240:241], s[0:1] offset:32
	v_add_f32_e32 v94, v94, v194
	v_add_f32_e32 v95, v95, v195
	v_add_f32_e32 v96, v96, v196
	v_add_f32_e32 v97, v97, v197
	v_add_f32_e32 v90, v90, v198
	v_add_f32_e32 v91, v91, v199
	v_add_f32_e32 v92, v92, v200
	v_add_f32_e32 v93, v93, v201
	v_add_f32_e32 v86, v86, v202
	v_add_f32_e32 v87, v87, v203
	v_add_f32_e32 v88, v88, v204
	v_add_f32_e32 v89, v89, v205
	v_add_f32_e32 v82, v82, v206
	v_add_f32_e32 v83, v83, v207
	v_add_f32_e32 v84, v84, v208
	v_add_f32_e32 v85, v85, v209
	s_cmp_lg_u32 s7, 0
	s_cbranch_scc0 .Lqv_nc2
	global_store_dwordx4 v248, v[94:97], s[82:83] offset:0
	global_store_dwordx4 v248, v[90:93], s[82:83] offset:64
	global_store_dwordx4 v248, v[86:89], s[82:83] offset:128
	global_store_dwordx4 v248, v[82:85], s[82:83] offset:192
	v_add_u32_e32 v248, 0x4000, v248
.Lqv_nc2:
	s_mov_b32 vcc_lo, 0x55555555
	s_mov_b32 vcc_hi, 0x55555555
	s_nop 1
	v_cndmask_b32_dpp v210, v95, v94, vcc quad_perm:[1,0,3,2] row_mask:0xf bank_mask:0xf
	v_cndmask_b32_dpp v212, v97, v96, vcc quad_perm:[1,0,3,2] row_mask:0xf bank_mask:0xf
	v_cndmask_b32_dpp v214, v91, v90, vcc quad_perm:[1,0,3,2] row_mask:0xf bank_mask:0xf
	v_cndmask_b32_dpp v216, v93, v92, vcc quad_perm:[1,0,3,2] row_mask:0xf bank_mask:0xf
	v_cndmask_b32_dpp v218, v87, v86, vcc quad_perm:[1,0,3,2] row_mask:0xf bank_mask:0xf
	v_cndmask_b32_dpp v220, v89, v88, vcc quad_perm:[1,0,3,2] row_mask:0xf bank_mask:0xf
	v_cndmask_b32_dpp v222, v83, v82, vcc quad_perm:[1,0,3,2] row_mask:0xf bank_mask:0xf
	v_cndmask_b32_dpp v224, v85, v84, vcc quad_perm:[1,0,3,2] row_mask:0xf bank_mask:0xf
	s_mov_b32 vcc_lo, 0xaaaaaaaa
	s_mov_b32 vcc_hi, 0xaaaaaaaa
	s_nop 1
	v_cndmask_b32_dpp v211, v94, v95, vcc quad_perm:[1,0,3,2] row_mask:0xf bank_mask:0xf
	v_cndmask_b32_dpp v213, v96, v97, vcc quad_perm:[1,0,3,2] row_mask:0xf bank_mask:0xf
	v_cndmask_b32_dpp v215, v90, v91, vcc quad_perm:[1,0,3,2] row_mask:0xf bank_mask:0xf
	v_cndmask_b32_dpp v217, v92, v93, vcc quad_perm:[1,0,3,2] row_mask:0xf bank_mask:0xf
	v_cndmask_b32_dpp v219, v86, v87, vcc quad_perm:[1,0,3,2] row_mask:0xf bank_mask:0xf
	v_cndmask_b32_dpp v221, v88, v89, vcc quad_perm:[1,0,3,2] row_mask:0xf bank_mask:0xf
	v_cndmask_b32_dpp v223, v82, v83, vcc quad_perm:[1,0,3,2] row_mask:0xf bank_mask:0xf
	v_cndmask_b32_dpp v225, v84, v85, vcc quad_perm:[1,0,3,2] row_mask:0xf bank_mask:0xf
	s_mov_b32 vcc_lo, 0x33333333
	s_mov_b32 vcc_hi, 0x33333333
	s_nop 1
	v_cndmask_b32_dpp v94, v212, v210, vcc quad_perm:[2,3,0,1] row_mask:0xf bank_mask:0xf
	v_cndmask_b32_dpp v95, v213, v211, vcc quad_perm:[2,3,0,1] row_mask:0xf bank_mask:0xf
	v_cndmask_b32_dpp v90, v216, v214, vcc quad_perm:[2,3,0,1] row_mask:0xf bank_mask:0xf
	v_cndmask_b32_dpp v91, v217, v215, vcc quad_perm:[2,3,0,1] row_mask:0xf bank_mask:0xf
	v_cndmask_b32_dpp v86, v220, v218, vcc quad_perm:[2,3,0,1] row_mask:0xf bank_mask:0xf
	v_cndmask_b32_dpp v87, v221, v219, vcc quad_perm:[2,3,0,1] row_mask:0xf bank_mask:0xf
	v_cndmask_b32_dpp v82, v224, v222, vcc quad_perm:[2,3,0,1] row_mask:0xf bank_mask:0xf
	v_cndmask_b32_dpp v83, v225, v223, vcc quad_perm:[2,3,0,1] row_mask:0xf bank_mask:0xf
	s_mov_b32 vcc_lo, 0xcccccccc
	s_mov_b32 vcc_hi, 0xcccccccc
	s_nop 1
	v_cndmask_b32_dpp v96, v210, v212, vcc quad_perm:[2,3,0,1] row_mask:0xf bank_mask:0xf
	v_cndmask_b32_dpp v97, v211, v213, vcc quad_perm:[2,3,0,1] row_mask:0xf bank_mask:0xf
	v_cndmask_b32_dpp v92, v214, v216, vcc quad_perm:[2,3,0,1] row_mask:0xf bank_mask:0xf
	v_cndmask_b32_dpp v93, v215, v217, vcc quad_perm:[2,3,0,1] row_mask:0xf bank_mask:0xf
	v_cndmask_b32_dpp v88, v218, v220, vcc quad_perm:[2,3,0,1] row_mask:0xf bank_mask:0xf
	v_cndmask_b32_dpp v89, v219, v221, vcc quad_perm:[2,3,0,1] row_mask:0xf bank_mask:0xf
	v_cndmask_b32_dpp v84, v222, v224, vcc quad_perm:[2,3,0,1] row_mask:0xf bank_mask:0xf
	v_cndmask_b32_dpp v85, v223, v225, vcc quad_perm:[2,3,0,1] row_mask:0xf bank_mask:0xf
	v_cvt_pk_bf16_f32 v226, v94, v95
	v_cvt_pk_bf16_f32 v227, v96, v97
	v_cvt_pk_bf16_f32 v228, v90, v91
	v_cvt_pk_bf16_f32 v229, v92, v93
	v_cvt_pk_bf16_f32 v230, v86, v87
	v_cvt_pk_bf16_f32 v231, v88, v89
	v_cvt_pk_bf16_f32 v232, v82, v83
	v_cvt_pk_bf16_f32 v233, v84, v85
	global_store_dwordx2 v242, v[226:227], s[0:1] offset:64
	global_store_dwordx2 v243, v[228:229], s[0:1] offset:64
	global_store_dwordx2 v244, v[230:231], s[0:1] offset:64
	global_store_dwordx2 v245, v[232:233], s[0:1] offset:64
	v_add_f32_e32 v78, v78, v194
	v_add_f32_e32 v79, v79, v195
	v_add_f32_e32 v80, v80, v196
	v_add_f32_e32 v81, v81, v197
	v_add_f32_e32 v74, v74, v198
	v_add_f32_e32 v75, v75, v199
	v_add_f32_e32 v76, v76, v200
	v_add_f32_e32 v77, v77, v201
	v_add_f32_e32 v70, v70, v202
	v_add_f32_e32 v71, v71, v203
	v_add_f32_e32 v72, v72, v204
	v_add_f32_e32 v73, v73, v205
	v_add_f32_e32 v66, v66, v206
	v_add_f32_e32 v67, v67, v207
	v_add_f32_e32 v68, v68, v208
	v_add_f32_e32 v69, v69, v209
	s_cmp_lg_u32 s7, 0
	s_cbranch_scc0 .Lqv_nc3
	global_store_dwordx4 v248, v[78:81], s[82:83] offset:0
	global_store_dwordx4 v248, v[74:77], s[82:83] offset:64
	global_store_dwordx4 v248, v[70:73], s[82:83] offset:128
	global_store_dwordx4 v248, v[66:69], s[82:83] offset:192
	v_add_u32_e32 v248, 0x4000, v248
.Lqv_nc3:
	s_mov_b32 vcc_lo, 0x55555555
	s_mov_b32 vcc_hi, 0x55555555
	s_nop 1
	v_cndmask_b32_dpp v210, v79, v78, vcc quad_perm:[1,0,3,2] row_mask:0xf bank_mask:0xf
	v_cndmask_b32_dpp v212, v81, v80, vcc quad_perm:[1,0,3,2] row_mask:0xf bank_mask:0xf
	v_cndmask_b32_dpp v214, v75, v74, vcc quad_perm:[1,0,3,2] row_mask:0xf bank_mask:0xf
	v_cndmask_b32_dpp v216, v77, v76, vcc quad_perm:[1,0,3,2] row_mask:0xf bank_mask:0xf
	v_cndmask_b32_dpp v218, v71, v70, vcc quad_perm:[1,0,3,2] row_mask:0xf bank_mask:0xf
	v_cndmask_b32_dpp v220, v73, v72, vcc quad_perm:[1,0,3,2] row_mask:0xf bank_mask:0xf
	v_cndmask_b32_dpp v222, v67, v66, vcc quad_perm:[1,0,3,2] row_mask:0xf bank_mask:0xf
	v_cndmask_b32_dpp v224, v69, v68, vcc quad_perm:[1,0,3,2] row_mask:0xf bank_mask:0xf
	s_mov_b32 vcc_lo, 0xaaaaaaaa
	s_mov_b32 vcc_hi, 0xaaaaaaaa
	s_nop 1
	v_cndmask_b32_dpp v211, v78, v79, vcc quad_perm:[1,0,3,2] row_mask:0xf bank_mask:0xf
	v_cndmask_b32_dpp v213, v80, v81, vcc quad_perm:[1,0,3,2] row_mask:0xf bank_mask:0xf
	v_cndmask_b32_dpp v215, v74, v75, vcc quad_perm:[1,0,3,2] row_mask:0xf bank_mask:0xf
	v_cndmask_b32_dpp v217, v76, v77, vcc quad_perm:[1,0,3,2] row_mask:0xf bank_mask:0xf
	v_cndmask_b32_dpp v219, v70, v71, vcc quad_perm:[1,0,3,2] row_mask:0xf bank_mask:0xf
	v_cndmask_b32_dpp v221, v72, v73, vcc quad_perm:[1,0,3,2] row_mask:0xf bank_mask:0xf
	v_cndmask_b32_dpp v223, v66, v67, vcc quad_perm:[1,0,3,2] row_mask:0xf bank_mask:0xf
	v_cndmask_b32_dpp v225, v68, v69, vcc quad_perm:[1,0,3,2] row_mask:0xf bank_mask:0xf
	s_mov_b32 vcc_lo, 0x33333333
	s_mov_b32 vcc_hi, 0x33333333
	s_nop 1
	v_cndmask_b32_dpp v78, v212, v210, vcc quad_perm:[2,3,0,1] row_mask:0xf bank_mask:0xf
	v_cndmask_b32_dpp v79, v213, v211, vcc quad_perm:[2,3,0,1] row_mask:0xf bank_mask:0xf
	v_cndmask_b32_dpp v74, v216, v214, vcc quad_perm:[2,3,0,1] row_mask:0xf bank_mask:0xf
	v_cndmask_b32_dpp v75, v217, v215, vcc quad_perm:[2,3,0,1] row_mask:0xf bank_mask:0xf
	v_cndmask_b32_dpp v70, v220, v218, vcc quad_perm:[2,3,0,1] row_mask:0xf bank_mask:0xf
	v_cndmask_b32_dpp v71, v221, v219, vcc quad_perm:[2,3,0,1] row_mask:0xf bank_mask:0xf
	v_cndmask_b32_dpp v66, v224, v222, vcc quad_perm:[2,3,0,1] row_mask:0xf bank_mask:0xf
	v_cndmask_b32_dpp v67, v225, v223, vcc quad_perm:[2,3,0,1] row_mask:0xf bank_mask:0xf
	s_mov_b32 vcc_lo, 0xcccccccc
	s_mov_b32 vcc_hi, 0xcccccccc
	s_nop 1
	v_cndmask_b32_dpp v80, v210, v212, vcc quad_perm:[2,3,0,1] row_mask:0xf bank_mask:0xf
	v_cndmask_b32_dpp v81, v211, v213, vcc quad_perm:[2,3,0,1] row_mask:0xf bank_mask:0xf
	v_cndmask_b32_dpp v76, v214, v216, vcc quad_perm:[2,3,0,1] row_mask:0xf bank_mask:0xf
	v_cndmask_b32_dpp v77, v215, v217, vcc quad_perm:[2,3,0,1] row_mask:0xf bank_mask:0xf
	v_cndmask_b32_dpp v72, v218, v220, vcc quad_perm:[2,3,0,1] row_mask:0xf bank_mask:0xf
	v_cndmask_b32_dpp v73, v219, v221, vcc quad_perm:[2,3,0,1] row_mask:0xf bank_mask:0xf
	v_cndmask_b32_dpp v68, v222, v224, vcc quad_perm:[2,3,0,1] row_mask:0xf bank_mask:0xf
	v_cndmask_b32_dpp v69, v223, v225, vcc quad_perm:[2,3,0,1] row_mask:0xf bank_mask:0xf
	v_cvt_pk_bf16_f32 v234, v78, v79
	v_cvt_pk_bf16_f32 v235, v80, v81
	v_cvt_pk_bf16_f32 v236, v74, v75
	v_cvt_pk_bf16_f32 v237, v76, v77
	v_cvt_pk_bf16_f32 v238, v70, v71
	v_cvt_pk_bf16_f32 v239, v72, v73
	v_cvt_pk_bf16_f32 v240, v66, v67
	v_cvt_pk_bf16_f32 v241, v68, v69
	global_store_dwordx2 v242, v[234:235], s[0:1] offset:96
	global_store_dwordx2 v243, v[236:237], s[0:1] offset:96
	global_store_dwordx2 v244, v[238:239], s[0:1] offset:96
	global_store_dwordx2 v245, v[240:241], s[0:1] offset:96
	v_add_f32_e32 v62, v62, v194
	v_add_f32_e32 v63, v63, v195
	v_add_f32_e32 v64, v64, v196
	v_add_f32_e32 v65, v65, v197
	v_add_f32_e32 v58, v58, v198
	v_add_f32_e32 v59, v59, v199
	v_add_f32_e32 v60, v60, v200
	v_add_f32_e32 v61, v61, v201
	v_add_f32_e32 v54, v54, v202
	v_add_f32_e32 v55, v55, v203
	v_add_f32_e32 v56, v56, v204
	v_add_f32_e32 v57, v57, v205
	v_add_f32_e32 v50, v50, v206
	v_add_f32_e32 v51, v51, v207
	v_add_f32_e32 v52, v52, v208
	v_add_f32_e32 v53, v53, v209
	s_cmp_lg_u32 s7, 0
	s_cbranch_scc0 .Lqv_nc4
	global_store_dwordx4 v248, v[62:65], s[82:83] offset:0
	global_store_dwordx4 v248, v[58:61], s[82:83] offset:64
	global_store_dwordx4 v248, v[54:57], s[82:83] offset:128
	global_store_dwordx4 v248, v[50:53], s[82:83] offset:192
	v_add_u32_e32 v248, 0x4000, v248
.Lqv_nc4:
	s_mov_b32 vcc_lo, 0x55555555
	s_mov_b32 vcc_hi, 0x55555555
	s_nop 1
	v_cndmask_b32_dpp v210, v63, v62, vcc quad_perm:[1,0,3,2] row_mask:0xf bank_mask:0xf
	v_cndmask_b32_dpp v212, v65, v64, vcc quad_perm:[1,0,3,2] row_mask:0xf bank_mask:0xf
	v_cndmask_b32_dpp v214, v59, v58, vcc quad_perm:[1,0,3,2] row_mask:0xf bank_mask:0xf
	v_cndmask_b32_dpp v216, v61, v60, vcc quad_perm:[1,0,3,2] row_mask:0xf bank_mask:0xf
	v_cndmask_b32_dpp v218, v55, v54, vcc quad_perm:[1,0,3,2] row_mask:0xf bank_mask:0xf
	v_cndmask_b32_dpp v220, v57, v56, vcc quad_perm:[1,0,3,2] row_mask:0xf bank_mask:0xf
	v_cndmask_b32_dpp v222, v51, v50, vcc quad_perm:[1,0,3,2] row_mask:0xf bank_mask:0xf
	v_cndmask_b32_dpp v224, v53, v52, vcc quad_perm:[1,0,3,2] row_mask:0xf bank_mask:0xf
	s_mov_b32 vcc_lo, 0xaaaaaaaa
	s_mov_b32 vcc_hi, 0xaaaaaaaa
	s_nop 1
	v_cndmask_b32_dpp v211, v62, v63, vcc quad_perm:[1,0,3,2] row_mask:0xf bank_mask:0xf
	v_cndmask_b32_dpp v213, v64, v65, vcc quad_perm:[1,0,3,2] row_mask:0xf bank_mask:0xf
	v_cndmask_b32_dpp v215, v58, v59, vcc quad_perm:[1,0,3,2] row_mask:0xf bank_mask:0xf
	v_cndmask_b32_dpp v217, v60, v61, vcc quad_perm:[1,0,3,2] row_mask:0xf bank_mask:0xf
	v_cndmask_b32_dpp v219, v54, v55, vcc quad_perm:[1,0,3,2] row_mask:0xf bank_mask:0xf
	v_cndmask_b32_dpp v221, v56, v57, vcc quad_perm:[1,0,3,2] row_mask:0xf bank_mask:0xf
	v_cndmask_b32_dpp v223, v50, v51, vcc quad_perm:[1,0,3,2] row_mask:0xf bank_mask:0xf
	v_cndmask_b32_dpp v225, v52, v53, vcc quad_perm:[1,0,3,2] row_mask:0xf bank_mask:0xf
	s_mov_b32 vcc_lo, 0x33333333
	s_mov_b32 vcc_hi, 0x33333333
	s_nop 1
	v_cndmask_b32_dpp v62, v212, v210, vcc quad_perm:[2,3,0,1] row_mask:0xf bank_mask:0xf
	v_cndmask_b32_dpp v63, v213, v211, vcc quad_perm:[2,3,0,1] row_mask:0xf bank_mask:0xf
	v_cndmask_b32_dpp v58, v216, v214, vcc quad_perm:[2,3,0,1] row_mask:0xf bank_mask:0xf
	v_cndmask_b32_dpp v59, v217, v215, vcc quad_perm:[2,3,0,1] row_mask:0xf bank_mask:0xf
	v_cndmask_b32_dpp v54, v220, v218, vcc quad_perm:[2,3,0,1] row_mask:0xf bank_mask:0xf
	v_cndmask_b32_dpp v55, v221, v219, vcc quad_perm:[2,3,0,1] row_mask:0xf bank_mask:0xf
	v_cndmask_b32_dpp v50, v224, v222, vcc quad_perm:[2,3,0,1] row_mask:0xf bank_mask:0xf
	v_cndmask_b32_dpp v51, v225, v223, vcc quad_perm:[2,3,0,1] row_mask:0xf bank_mask:0xf
	s_mov_b32 vcc_lo, 0xcccccccc
	s_mov_b32 vcc_hi, 0xcccccccc
	s_nop 1
	v_cndmask_b32_dpp v64, v210, v212, vcc quad_perm:[2,3,0,1] row_mask:0xf bank_mask:0xf
	v_cndmask_b32_dpp v65, v211, v213, vcc quad_perm:[2,3,0,1] row_mask:0xf bank_mask:0xf
	v_cndmask_b32_dpp v60, v214, v216, vcc quad_perm:[2,3,0,1] row_mask:0xf bank_mask:0xf
	v_cndmask_b32_dpp v61, v215, v217, vcc quad_perm:[2,3,0,1] row_mask:0xf bank_mask:0xf
	v_cndmask_b32_dpp v56, v218, v220, vcc quad_perm:[2,3,0,1] row_mask:0xf bank_mask:0xf
	v_cndmask_b32_dpp v57, v219, v221, vcc quad_perm:[2,3,0,1] row_mask:0xf bank_mask:0xf
	v_cndmask_b32_dpp v52, v222, v224, vcc quad_perm:[2,3,0,1] row_mask:0xf bank_mask:0xf
	v_cndmask_b32_dpp v53, v223, v225, vcc quad_perm:[2,3,0,1] row_mask:0xf bank_mask:0xf
	v_cvt_pk_bf16_f32 v226, v62, v63
	v_cvt_pk_bf16_f32 v227, v64, v65
	v_cvt_pk_bf16_f32 v228, v58, v59
	v_cvt_pk_bf16_f32 v229, v60, v61
	v_cvt_pk_bf16_f32 v230, v54, v55
	v_cvt_pk_bf16_f32 v231, v56, v57
	v_cvt_pk_bf16_f32 v232, v50, v51
	v_cvt_pk_bf16_f32 v233, v52, v53
	global_store_dwordx2 v242, v[226:227], s[0:1] offset:128
	global_store_dwordx2 v243, v[228:229], s[0:1] offset:128
	global_store_dwordx2 v244, v[230:231], s[0:1] offset:128
	global_store_dwordx2 v245, v[232:233], s[0:1] offset:128
	v_add_f32_e32 v46, v46, v194
	v_add_f32_e32 v47, v47, v195
	v_add_f32_e32 v48, v48, v196
	v_add_f32_e32 v49, v49, v197
	v_add_f32_e32 v42, v42, v198
	v_add_f32_e32 v43, v43, v199
	v_add_f32_e32 v44, v44, v200
	v_add_f32_e32 v45, v45, v201
	v_add_f32_e32 v38, v38, v202
	v_add_f32_e32 v39, v39, v203
	v_add_f32_e32 v40, v40, v204
	v_add_f32_e32 v41, v41, v205
	v_add_f32_e32 v34, v34, v206
	v_add_f32_e32 v35, v35, v207
	v_add_f32_e32 v36, v36, v208
	v_add_f32_e32 v37, v37, v209
	s_cmp_lg_u32 s7, 0
	s_cbranch_scc0 .Lqv_nc5
	global_store_dwordx4 v248, v[46:49], s[82:83] offset:0
	global_store_dwordx4 v248, v[42:45], s[82:83] offset:64
	global_store_dwordx4 v248, v[38:41], s[82:83] offset:128
	global_store_dwordx4 v248, v[34:37], s[82:83] offset:192
	v_add_u32_e32 v248, 0x4000, v248
.Lqv_nc5:
	s_mov_b32 vcc_lo, 0x55555555
	s_mov_b32 vcc_hi, 0x55555555
	s_nop 1
	v_cndmask_b32_dpp v210, v47, v46, vcc quad_perm:[1,0,3,2] row_mask:0xf bank_mask:0xf
	v_cndmask_b32_dpp v212, v49, v48, vcc quad_perm:[1,0,3,2] row_mask:0xf bank_mask:0xf
	v_cndmask_b32_dpp v214, v43, v42, vcc quad_perm:[1,0,3,2] row_mask:0xf bank_mask:0xf
	v_cndmask_b32_dpp v216, v45, v44, vcc quad_perm:[1,0,3,2] row_mask:0xf bank_mask:0xf
	v_cndmask_b32_dpp v218, v39, v38, vcc quad_perm:[1,0,3,2] row_mask:0xf bank_mask:0xf
	v_cndmask_b32_dpp v220, v41, v40, vcc quad_perm:[1,0,3,2] row_mask:0xf bank_mask:0xf
	v_cndmask_b32_dpp v222, v35, v34, vcc quad_perm:[1,0,3,2] row_mask:0xf bank_mask:0xf
	v_cndmask_b32_dpp v224, v37, v36, vcc quad_perm:[1,0,3,2] row_mask:0xf bank_mask:0xf
	s_mov_b32 vcc_lo, 0xaaaaaaaa
	s_mov_b32 vcc_hi, 0xaaaaaaaa
	s_nop 1
	v_cndmask_b32_dpp v211, v46, v47, vcc quad_perm:[1,0,3,2] row_mask:0xf bank_mask:0xf
	v_cndmask_b32_dpp v213, v48, v49, vcc quad_perm:[1,0,3,2] row_mask:0xf bank_mask:0xf
	v_cndmask_b32_dpp v215, v42, v43, vcc quad_perm:[1,0,3,2] row_mask:0xf bank_mask:0xf
	v_cndmask_b32_dpp v217, v44, v45, vcc quad_perm:[1,0,3,2] row_mask:0xf bank_mask:0xf
	v_cndmask_b32_dpp v219, v38, v39, vcc quad_perm:[1,0,3,2] row_mask:0xf bank_mask:0xf
	v_cndmask_b32_dpp v221, v40, v41, vcc quad_perm:[1,0,3,2] row_mask:0xf bank_mask:0xf
	v_cndmask_b32_dpp v223, v34, v35, vcc quad_perm:[1,0,3,2] row_mask:0xf bank_mask:0xf
	v_cndmask_b32_dpp v225, v36, v37, vcc quad_perm:[1,0,3,2] row_mask:0xf bank_mask:0xf
	s_mov_b32 vcc_lo, 0x33333333
	s_mov_b32 vcc_hi, 0x33333333
	s_nop 1
	v_cndmask_b32_dpp v46, v212, v210, vcc quad_perm:[2,3,0,1] row_mask:0xf bank_mask:0xf
	v_cndmask_b32_dpp v47, v213, v211, vcc quad_perm:[2,3,0,1] row_mask:0xf bank_mask:0xf
	v_cndmask_b32_dpp v42, v216, v214, vcc quad_perm:[2,3,0,1] row_mask:0xf bank_mask:0xf
	v_cndmask_b32_dpp v43, v217, v215, vcc quad_perm:[2,3,0,1] row_mask:0xf bank_mask:0xf
	v_cndmask_b32_dpp v38, v220, v218, vcc quad_perm:[2,3,0,1] row_mask:0xf bank_mask:0xf
	v_cndmask_b32_dpp v39, v221, v219, vcc quad_perm:[2,3,0,1] row_mask:0xf bank_mask:0xf
	v_cndmask_b32_dpp v34, v224, v222, vcc quad_perm:[2,3,0,1] row_mask:0xf bank_mask:0xf
	v_cndmask_b32_dpp v35, v225, v223, vcc quad_perm:[2,3,0,1] row_mask:0xf bank_mask:0xf
	s_mov_b32 vcc_lo, 0xcccccccc
	s_mov_b32 vcc_hi, 0xcccccccc
	s_nop 1
	v_cndmask_b32_dpp v48, v210, v212, vcc quad_perm:[2,3,0,1] row_mask:0xf bank_mask:0xf
	v_cndmask_b32_dpp v49, v211, v213, vcc quad_perm:[2,3,0,1] row_mask:0xf bank_mask:0xf
	v_cndmask_b32_dpp v44, v214, v216, vcc quad_perm:[2,3,0,1] row_mask:0xf bank_mask:0xf
	v_cndmask_b32_dpp v45, v215, v217, vcc quad_perm:[2,3,0,1] row_mask:0xf bank_mask:0xf
	v_cndmask_b32_dpp v40, v218, v220, vcc quad_perm:[2,3,0,1] row_mask:0xf bank_mask:0xf
	v_cndmask_b32_dpp v41, v219, v221, vcc quad_perm:[2,3,0,1] row_mask:0xf bank_mask:0xf
	v_cndmask_b32_dpp v36, v222, v224, vcc quad_perm:[2,3,0,1] row_mask:0xf bank_mask:0xf
	v_cndmask_b32_dpp v37, v223, v225, vcc quad_perm:[2,3,0,1] row_mask:0xf bank_mask:0xf
	v_cvt_pk_bf16_f32 v234, v46, v47
	v_cvt_pk_bf16_f32 v235, v48, v49
	v_cvt_pk_bf16_f32 v236, v42, v43
	v_cvt_pk_bf16_f32 v237, v44, v45
	v_cvt_pk_bf16_f32 v238, v38, v39
	v_cvt_pk_bf16_f32 v239, v40, v41
	v_cvt_pk_bf16_f32 v240, v34, v35
	v_cvt_pk_bf16_f32 v241, v36, v37
	global_store_dwordx2 v242, v[234:235], s[0:1] offset:160
	global_store_dwordx2 v243, v[236:237], s[0:1] offset:160
	global_store_dwordx2 v244, v[238:239], s[0:1] offset:160
	global_store_dwordx2 v245, v[240:241], s[0:1] offset:160
	v_add_f32_e32 v30, v30, v194
	v_add_f32_e32 v31, v31, v195
	v_add_f32_e32 v32, v32, v196
	v_add_f32_e32 v33, v33, v197
	v_add_f32_e32 v26, v26, v198
	v_add_f32_e32 v27, v27, v199
	v_add_f32_e32 v28, v28, v200
	v_add_f32_e32 v29, v29, v201
	v_add_f32_e32 v22, v22, v202
	v_add_f32_e32 v23, v23, v203
	v_add_f32_e32 v24, v24, v204
	v_add_f32_e32 v25, v25, v205
	v_add_f32_e32 v18, v18, v206
	v_add_f32_e32 v19, v19, v207
	v_add_f32_e32 v20, v20, v208
	v_add_f32_e32 v21, v21, v209
	s_cmp_lg_u32 s7, 0
	s_cbranch_scc0 .Lqv_nc6
	global_store_dwordx4 v248, v[30:33], s[82:83] offset:0
	global_store_dwordx4 v248, v[26:29], s[82:83] offset:64
	global_store_dwordx4 v248, v[22:25], s[82:83] offset:128
	global_store_dwordx4 v248, v[18:21], s[82:83] offset:192
	v_add_u32_e32 v248, 0x4000, v248
.Lqv_nc6:
	s_mov_b32 vcc_lo, 0x55555555
	s_mov_b32 vcc_hi, 0x55555555
	s_nop 1
	v_cndmask_b32_dpp v210, v31, v30, vcc quad_perm:[1,0,3,2] row_mask:0xf bank_mask:0xf
	v_cndmask_b32_dpp v212, v33, v32, vcc quad_perm:[1,0,3,2] row_mask:0xf bank_mask:0xf
	v_cndmask_b32_dpp v214, v27, v26, vcc quad_perm:[1,0,3,2] row_mask:0xf bank_mask:0xf
	v_cndmask_b32_dpp v216, v29, v28, vcc quad_perm:[1,0,3,2] row_mask:0xf bank_mask:0xf
	v_cndmask_b32_dpp v218, v23, v22, vcc quad_perm:[1,0,3,2] row_mask:0xf bank_mask:0xf
	v_cndmask_b32_dpp v220, v25, v24, vcc quad_perm:[1,0,3,2] row_mask:0xf bank_mask:0xf
	v_cndmask_b32_dpp v222, v19, v18, vcc quad_perm:[1,0,3,2] row_mask:0xf bank_mask:0xf
	v_cndmask_b32_dpp v224, v21, v20, vcc quad_perm:[1,0,3,2] row_mask:0xf bank_mask:0xf
	s_mov_b32 vcc_lo, 0xaaaaaaaa
	s_mov_b32 vcc_hi, 0xaaaaaaaa
	s_nop 1
	v_cndmask_b32_dpp v211, v30, v31, vcc quad_perm:[1,0,3,2] row_mask:0xf bank_mask:0xf
	v_cndmask_b32_dpp v213, v32, v33, vcc quad_perm:[1,0,3,2] row_mask:0xf bank_mask:0xf
	v_cndmask_b32_dpp v215, v26, v27, vcc quad_perm:[1,0,3,2] row_mask:0xf bank_mask:0xf
	v_cndmask_b32_dpp v217, v28, v29, vcc quad_perm:[1,0,3,2] row_mask:0xf bank_mask:0xf
	v_cndmask_b32_dpp v219, v22, v23, vcc quad_perm:[1,0,3,2] row_mask:0xf bank_mask:0xf
	v_cndmask_b32_dpp v221, v24, v25, vcc quad_perm:[1,0,3,2] row_mask:0xf bank_mask:0xf
	v_cndmask_b32_dpp v223, v18, v19, vcc quad_perm:[1,0,3,2] row_mask:0xf bank_mask:0xf
	v_cndmask_b32_dpp v225, v20, v21, vcc quad_perm:[1,0,3,2] row_mask:0xf bank_mask:0xf
	s_mov_b32 vcc_lo, 0x33333333
	s_mov_b32 vcc_hi, 0x33333333
	s_nop 1
	v_cndmask_b32_dpp v30, v212, v210, vcc quad_perm:[2,3,0,1] row_mask:0xf bank_mask:0xf
	v_cndmask_b32_dpp v31, v213, v211, vcc quad_perm:[2,3,0,1] row_mask:0xf bank_mask:0xf
	v_cndmask_b32_dpp v26, v216, v214, vcc quad_perm:[2,3,0,1] row_mask:0xf bank_mask:0xf
	v_cndmask_b32_dpp v27, v217, v215, vcc quad_perm:[2,3,0,1] row_mask:0xf bank_mask:0xf
	v_cndmask_b32_dpp v22, v220, v218, vcc quad_perm:[2,3,0,1] row_mask:0xf bank_mask:0xf
	v_cndmask_b32_dpp v23, v221, v219, vcc quad_perm:[2,3,0,1] row_mask:0xf bank_mask:0xf
	v_cndmask_b32_dpp v18, v224, v222, vcc quad_perm:[2,3,0,1] row_mask:0xf bank_mask:0xf
	v_cndmask_b32_dpp v19, v225, v223, vcc quad_perm:[2,3,0,1] row_mask:0xf bank_mask:0xf
	s_mov_b32 vcc_lo, 0xcccccccc
	s_mov_b32 vcc_hi, 0xcccccccc
	s_nop 1
	v_cndmask_b32_dpp v32, v210, v212, vcc quad_perm:[2,3,0,1] row_mask:0xf bank_mask:0xf
	v_cndmask_b32_dpp v33, v211, v213, vcc quad_perm:[2,3,0,1] row_mask:0xf bank_mask:0xf
	v_cndmask_b32_dpp v28, v214, v216, vcc quad_perm:[2,3,0,1] row_mask:0xf bank_mask:0xf
	v_cndmask_b32_dpp v29, v215, v217, vcc quad_perm:[2,3,0,1] row_mask:0xf bank_mask:0xf
	v_cndmask_b32_dpp v24, v218, v220, vcc quad_perm:[2,3,0,1] row_mask:0xf bank_mask:0xf
	v_cndmask_b32_dpp v25, v219, v221, vcc quad_perm:[2,3,0,1] row_mask:0xf bank_mask:0xf
	v_cndmask_b32_dpp v20, v222, v224, vcc quad_perm:[2,3,0,1] row_mask:0xf bank_mask:0xf
	v_cndmask_b32_dpp v21, v223, v225, vcc quad_perm:[2,3,0,1] row_mask:0xf bank_mask:0xf
	v_cvt_pk_bf16_f32 v226, v30, v31
	v_cvt_pk_bf16_f32 v227, v32, v33
	v_cvt_pk_bf16_f32 v228, v26, v27
	v_cvt_pk_bf16_f32 v229, v28, v29
	v_cvt_pk_bf16_f32 v230, v22, v23
	v_cvt_pk_bf16_f32 v231, v24, v25
	v_cvt_pk_bf16_f32 v232, v18, v19
	v_cvt_pk_bf16_f32 v233, v20, v21
	global_store_dwordx2 v242, v[226:227], s[0:1] offset:192
	global_store_dwordx2 v243, v[228:229], s[0:1] offset:192
	global_store_dwordx2 v244, v[230:231], s[0:1] offset:192
	global_store_dwordx2 v245, v[232:233], s[0:1] offset:192
	v_add_f32_e32 v14, v14, v194
	v_add_f32_e32 v15, v15, v195
	v_add_f32_e32 v16, v16, v196
	v_add_f32_e32 v17, v17, v197
	v_add_f32_e32 v10, v10, v198
	v_add_f32_e32 v11, v11, v199
	v_add_f32_e32 v12, v12, v200
	v_add_f32_e32 v13, v13, v201
	v_add_f32_e32 v6, v6, v202
	v_add_f32_e32 v7, v7, v203
	v_add_f32_e32 v8, v8, v204
	v_add_f32_e32 v9, v9, v205
	v_add_f32_e32 v2, v2, v206
	v_add_f32_e32 v3, v3, v207
	v_add_f32_e32 v4, v4, v208
	v_add_f32_e32 v5, v5, v209
	s_cmp_lg_u32 s7, 0
	s_cbranch_scc0 .Lqv_nc7
	global_store_dwordx4 v248, v[14:17], s[82:83] offset:0
	global_store_dwordx4 v248, v[10:13], s[82:83] offset:64
	global_store_dwordx4 v248, v[6:9], s[82:83] offset:128
	global_store_dwordx4 v248, v[2:5], s[82:83] offset:192
	v_add_u32_e32 v248, 0x4000, v248
.Lqv_nc7:
	s_mov_b32 vcc_lo, 0x55555555
	s_mov_b32 vcc_hi, 0x55555555
	s_nop 1
	v_cndmask_b32_dpp v210, v15, v14, vcc quad_perm:[1,0,3,2] row_mask:0xf bank_mask:0xf
	v_cndmask_b32_dpp v212, v17, v16, vcc quad_perm:[1,0,3,2] row_mask:0xf bank_mask:0xf
	v_cndmask_b32_dpp v214, v11, v10, vcc quad_perm:[1,0,3,2] row_mask:0xf bank_mask:0xf
	v_cndmask_b32_dpp v216, v13, v12, vcc quad_perm:[1,0,3,2] row_mask:0xf bank_mask:0xf
	v_cndmask_b32_dpp v218, v7, v6, vcc quad_perm:[1,0,3,2] row_mask:0xf bank_mask:0xf
	v_cndmask_b32_dpp v220, v9, v8, vcc quad_perm:[1,0,3,2] row_mask:0xf bank_mask:0xf
	v_cndmask_b32_dpp v222, v3, v2, vcc quad_perm:[1,0,3,2] row_mask:0xf bank_mask:0xf
	v_cndmask_b32_dpp v224, v5, v4, vcc quad_perm:[1,0,3,2] row_mask:0xf bank_mask:0xf
	s_mov_b32 vcc_lo, 0xaaaaaaaa
	s_mov_b32 vcc_hi, 0xaaaaaaaa
	s_nop 1
	v_cndmask_b32_dpp v211, v14, v15, vcc quad_perm:[1,0,3,2] row_mask:0xf bank_mask:0xf
	v_cndmask_b32_dpp v213, v16, v17, vcc quad_perm:[1,0,3,2] row_mask:0xf bank_mask:0xf
	v_cndmask_b32_dpp v215, v10, v11, vcc quad_perm:[1,0,3,2] row_mask:0xf bank_mask:0xf
	v_cndmask_b32_dpp v217, v12, v13, vcc quad_perm:[1,0,3,2] row_mask:0xf bank_mask:0xf
	v_cndmask_b32_dpp v219, v6, v7, vcc quad_perm:[1,0,3,2] row_mask:0xf bank_mask:0xf
	v_cndmask_b32_dpp v221, v8, v9, vcc quad_perm:[1,0,3,2] row_mask:0xf bank_mask:0xf
	v_cndmask_b32_dpp v223, v2, v3, vcc quad_perm:[1,0,3,2] row_mask:0xf bank_mask:0xf
	v_cndmask_b32_dpp v225, v4, v5, vcc quad_perm:[1,0,3,2] row_mask:0xf bank_mask:0xf
	s_mov_b32 vcc_lo, 0x33333333
	s_mov_b32 vcc_hi, 0x33333333
	s_nop 1
	v_cndmask_b32_dpp v14, v212, v210, vcc quad_perm:[2,3,0,1] row_mask:0xf bank_mask:0xf
	v_cndmask_b32_dpp v15, v213, v211, vcc quad_perm:[2,3,0,1] row_mask:0xf bank_mask:0xf
	v_cndmask_b32_dpp v10, v216, v214, vcc quad_perm:[2,3,0,1] row_mask:0xf bank_mask:0xf
	v_cndmask_b32_dpp v11, v217, v215, vcc quad_perm:[2,3,0,1] row_mask:0xf bank_mask:0xf
	v_cndmask_b32_dpp v6, v220, v218, vcc quad_perm:[2,3,0,1] row_mask:0xf bank_mask:0xf
	v_cndmask_b32_dpp v7, v221, v219, vcc quad_perm:[2,3,0,1] row_mask:0xf bank_mask:0xf
	v_cndmask_b32_dpp v2, v224, v222, vcc quad_perm:[2,3,0,1] row_mask:0xf bank_mask:0xf
	v_cndmask_b32_dpp v3, v225, v223, vcc quad_perm:[2,3,0,1] row_mask:0xf bank_mask:0xf
	s_mov_b32 vcc_lo, 0xcccccccc
	s_mov_b32 vcc_hi, 0xcccccccc
	s_nop 1
	v_cndmask_b32_dpp v16, v210, v212, vcc quad_perm:[2,3,0,1] row_mask:0xf bank_mask:0xf
	v_cndmask_b32_dpp v17, v211, v213, vcc quad_perm:[2,3,0,1] row_mask:0xf bank_mask:0xf
	v_cndmask_b32_dpp v12, v214, v216, vcc quad_perm:[2,3,0,1] row_mask:0xf bank_mask:0xf
	v_cndmask_b32_dpp v13, v215, v217, vcc quad_perm:[2,3,0,1] row_mask:0xf bank_mask:0xf
	v_cndmask_b32_dpp v8, v218, v220, vcc quad_perm:[2,3,0,1] row_mask:0xf bank_mask:0xf
	v_cndmask_b32_dpp v9, v219, v221, vcc quad_perm:[2,3,0,1] row_mask:0xf bank_mask:0xf
	v_cndmask_b32_dpp v4, v222, v224, vcc quad_perm:[2,3,0,1] row_mask:0xf bank_mask:0xf
	v_cndmask_b32_dpp v5, v223, v225, vcc quad_perm:[2,3,0,1] row_mask:0xf bank_mask:0xf
	v_cvt_pk_bf16_f32 v234, v14, v15
	v_cvt_pk_bf16_f32 v235, v16, v17
	v_cvt_pk_bf16_f32 v236, v10, v11
	v_cvt_pk_bf16_f32 v237, v12, v13
	v_cvt_pk_bf16_f32 v238, v6, v7
	v_cvt_pk_bf16_f32 v239, v8, v9
	v_cvt_pk_bf16_f32 v240, v2, v3
	v_cvt_pk_bf16_f32 v241, v4, v5
	global_store_dwordx2 v242, v[234:235], s[0:1] offset:224
	global_store_dwordx2 v243, v[236:237], s[0:1] offset:224
	global_store_dwordx2 v244, v[238:239], s[0:1] offset:224
	global_store_dwordx2 v245, v[240:241], s[0:1] offset:224
	s_mov_b64 s[10:11], exec
	s_branch .LBB0_1912
.Lqv_orig:
	s_cmpk_lt_i32 s8, 0x500
	v_lshl_add_u64 v[132:133], v[130:131], 2, s[68:69]
	global_load_dwordx4 v[138:141], v[132:133], off
	v_lshl_or_b32 v151, s5, 7, v176
	v_lshlrev_b32_e32 v0, 3, v172
	s_cselect_b64 s[10:11], -1, 0
	s_cmpk_gt_i32 s8, 0x4ff
	v_and_b32_e32 v0, 8, v0
	v_add_u32_e32 v136, s62, v151
	s_cselect_b64 s[30:31], -1, 0
	v_cmp_gt_u32_e64 s[6:7], 32, v173
	v_mbcnt_hi_u32_b32 v150, -1, v175
	v_cmp_gt_i32_e64 s[4:5], s43, v136
	v_cmp_lt_i32_e64 s[0:1], s47, v136
	v_and_b32_e32 v152, 0xf8f, v136
	v_lshlrev_b32_e32 v134, 2, v0
	s_and_b64 vcc, exec, s[30:31]
	v_readlane_b32 s65, v192, 1
	v_readlane_b32 s66, v192, 2
	v_readlane_b32 s67, v192, 3
	v_readlane_b32 s70, v192, 6
	v_readlane_b32 s71, v192, 7
	s_waitcnt vmcnt(0)
	v_pk_add_f32 v[126:127], v[126:127], v[138:139]
	v_pk_add_f32 v[128:129], v[128:129], v[140:141]
	s_cbranch_vccnz .LBB0_1919
	v_lshlrev_b32_e32 v0, 4, v152
	v_cndmask_b32_e64 v0, v170, v0, s[4:5]
	v_lshlrev_b32_e32 v0, 2, v0
	v_lshl_add_u64 v[138:139], s[16:17], 0, v[0:1]
	v_mov_b32_e32 v135, v1
	v_lshl_add_u64 v[142:143], v[138:139], 0, v[134:135]
	global_load_dwordx4 v[138:141], v[142:143], off
	s_nop 0
	global_load_dwordx4 v[142:145], v[142:143], off offset:16
	v_and_b32_e32 v135, 64, v150
	v_xor_b32_e32 v0, 32, v150
	v_add_u32_e32 v135, 64, v135
	v_cmp_lt_i32_e32 vcc, v0, v135
	s_waitcnt vmcnt(1)
	v_mov_b32_e32 v155, v140
	v_cndmask_b32_e32 v0, v150, v0, vcc
	v_lshlrev_b32_e32 v0, 2, v0
	ds_bpermute_b32 v146, v0, v126
	ds_bpermute_b32 v147, v0, v127
	ds_bpermute_b32 v148, v0, v128
	ds_bpermute_b32 v149, v0, v129
	v_mov_b32_e32 v140, v139
	s_waitcnt vmcnt(0)
	v_mov_b32_e32 v139, v144
	v_mov_b32_e32 v144, v143
	v_mov_b32_e32 v154, v138
	v_mov_b32_e32 v138, v142
	s_waitcnt lgkmcnt(2)
	v_pk_mul_f32 v[140:141], v[140:141], v[146:147]
	s_waitcnt lgkmcnt(0)
	v_pk_mul_f32 v[142:143], v[144:145], v[148:149]
	v_cndmask_b32_e64 v141, v141, -v141, s[6:7]
	v_cndmask_b32_e64 v140, v140, -v140, s[6:7]
	v_cndmask_b32_e64 v143, v143, -v143, s[6:7]
	v_cndmask_b32_e64 v142, v142, -v142, s[6:7]
	v_pk_fma_f32 v[126:127], v[126:127], v[154:155], v[140:141]
	v_pk_fma_f32 v[128:129], v[128:129], v[138:139], v[142:143]

.LBB0_2753:
	s_and_b32 vcc_lo, s19, 7
	s_lshl_b32 vcc_lo, vcc_lo, 5
	s_lshr_b32 vcc_hi, s19, 3
	s_or_b32 vcc_lo, vcc_lo, vcc_hi
	s_cmpk_lt_i32 s19, 0x100
	s_cselect_b32 vcc_lo, vcc_lo, s19
	s_cmpk_lt_i32 s19, 0x100
	s_cselect_b64 s[8:9], -1, 0
	s_lshl_b32 s1, vcc_lo, 8
	s_and_b32 s10, s1, 0x300
	s_lshl_b32 s1, s19, 4
	s_lshl_b32 s0, vcc_lo, 6
	s_andn2_b32 s1, s1, 63
	s_and_b32 s0, s0, 0xffffff00
	s_addk_i32 s1, 0xf000
	s_cmpk_gt_i32 s19, 0xff
	s_cselect_b32 s20, 0x4000, s0
	s_cselect_b32 s0, s1, 0
	s_cselect_b32 s11, 2, 32
	s_cselect_b32 s6, 64, 0x80
	s_ashr_i32 s1, s0, 31
	s_lshl_b64 s[0:1], s[0:1], 1
	s_add_u32 s22, s60, s0
	s_waitcnt vmcnt(1)
	v_mov_b32_e32 v10, v174
	s_addc_u32 s23, s61, s1
	v_readlane_b32 s24, v192, 31
	v_readlane_b32 s25, v192, 32
	v_readfirstlane_b32 s13, v10
	s_add_u32 s0, s24, s0
	s_addc_u32 s1, s25, s1
	s_ashr_i32 s21, s13, 6
	v_bfe_u32 v0, v10, 2, 4
	s_lshl_b32 s24, s21, 4
	v_or_b32_e32 v2, s20, v0
	s_add_i32 s25, s24, 0x80
	v_or_b32_e32 v0, s10, v0
	s_and_b32 s12, s21, 3
	v_add_u32_e32 v12, s24, v2
	v_add_u32_e32 v4, s25, v2
	v_mov_b64_e32 v[2:3], s[22:23]
	s_waitcnt vmcnt(0)
	v_add_u32_e32 v8, s24, v0
	v_mov_b64_e32 v[6:7], s[0:1]
	v_add_u32_e32 v0, s25, v0
	s_ashr_i32 s13, s13, 8
	v_bfe_u32 v166, v10, 4, 2
	v_mad_i64_i32 v[4:5], s[22:23], v4, s14, v[2:3]
	v_mad_i64_i32 v[8:9], s[0:1], v8, s14, v[6:7]
	v_mad_i64_i32 v[6:7], s[0:1], v0, s14, v[6:7]
	v_mad_i64_i32 v[2:3], s[0:1], v12, s14, v[2:3]
	s_cmp_lg_u32 s13, 1
	v_bitop3_b32 v11, v166, v10, 3 bitop3:0x78
	s_cselect_b64 s[0:1], -1, 0
	s_lshl_b32 s22, s21, 10
	v_lshlrev_b32_e32 v0, 4, v11
	s_add_i32 s21, s22, 0
	v_lshl_add_u64 v[158:159], v[2:3], 0, v[0:1]
	s_mov_b32 m0, s21
	v_lshl_add_u64 v[160:161], v[4:5], 0, v[0:1]
	global_load_lds_dwordx4 v[158:159], off
	s_add_i32 m0, s21, 0x2000
	v_lshl_add_u64 v[162:163], v[8:9], 0, v[0:1]
	global_load_lds_dwordx4 v[160:161], off
	s_add_i32 m0, s21, 0x4000
	v_lshl_add_u64 v[164:165], v[6:7], 0, v[0:1]
	global_load_lds_dwordx4 v[162:163], off
	s_add_i32 m0, s21, 0x6000
	v_lshl_add_u64 v[2:3], v[158:159], 0, 64
	global_load_lds_dwordx4 v[164:165], off
	s_add_i32 m0, s21, 0x8000
	s_add_i32 s23, s22, 0x2000
	global_load_lds_dwordx4 v[2:3], off
	v_lshl_add_u64 v[2:3], v[160:161], 0, 64
	s_add_i32 m0, s21, 0xa000
	v_lshrrev_b32_e32 v0, 2, v10
	global_load_lds_dwordx4 v[2:3], off
	v_lshl_add_u64 v[2:3], v[162:163], 0, 64
	s_add_i32 m0, s21, 0xc000
	v_bitop3_b32 v0, v166, v0, 3 bitop3:0x78
	global_load_lds_dwordx4 v[2:3], off
	v_lshl_add_u64 v[2:3], v[164:165], 0, 64
	s_add_i32 m0, s21, 0xe000
	s_or_b64 s[0:1], s[8:9], s[0:1]
	global_load_lds_dwordx4 v[2:3], off
	v_lshl_add_u64 v[2:3], v[158:159], 0, s[6:7]
	s_add_i32 m0, s16, s22
	v_and_b32_e32 v167, 15, v10
	global_load_lds_dwordx4 v[2:3], off
	v_lshl_add_u64 v[2:3], v[160:161], 0, s[6:7]
	s_add_i32 m0, s16, s23
	v_lshlrev_b32_e32 v169, 4, v0
	global_load_lds_dwordx4 v[2:3], off
	v_lshl_add_u64 v[2:3], v[162:163], 0, s[6:7]
	s_add_i32 m0, s17, s22
	v_mov_b32_e32 v0, v1
	global_load_lds_dwordx4 v[2:3], off
	v_lshl_add_u64 v[2:3], v[164:165], 0, s[6:7]
	s_add_i32 m0, s17, s23
	v_cndmask_b32_e64 v4, 0, 1, s[0:1]
	global_load_lds_dwordx4 v[2:3], off
	s_waitcnt vmcnt(8)
	v_mov_b32_e32 v2, v1
	v_mov_b32_e32 v3, v1
	s_waitcnt lgkmcnt(0)
	s_barrier
	v_mov_b64_e32 v[20:21], v[2:3]
	v_mov_b64_e32 v[24:25], v[2:3]
	v_mov_b64_e32 v[28:29], v[2:3]
	v_mov_b64_e32 v[32:33], v[2:3]
	v_mov_b64_e32 v[36:37], v[2:3]
	v_mov_b64_e32 v[40:41], v[2:3]
	v_mov_b64_e32 v[44:45], v[2:3]
	v_mov_b64_e32 v[48:49], v[2:3]
	v_mov_b64_e32 v[52:53], v[2:3]
	v_mov_b64_e32 v[56:57], v[2:3]
	v_mov_b64_e32 v[60:61], v[2:3]
	v_mov_b64_e32 v[64:65], v[2:3]
	v_mov_b64_e32 v[68:69], v[2:3]
	v_mov_b64_e32 v[72:73], v[2:3]
	v_mov_b64_e32 v[76:77], v[2:3]
	v_mov_b64_e32 v[80:81], v[2:3]
	v_mov_b64_e32 v[84:85], v[2:3]
	v_mov_b64_e32 v[88:89], v[2:3]
	v_mov_b64_e32 v[92:93], v[2:3]
	v_mov_b64_e32 v[96:97], v[2:3]
	v_mov_b64_e32 v[100:101], v[2:3]
	v_mov_b64_e32 v[104:105], v[2:3]
	v_mov_b64_e32 v[108:109], v[2:3]
	v_mov_b64_e32 v[112:113], v[2:3]
	v_mov_b64_e32 v[116:117], v[2:3]
	v_mov_b64_e32 v[120:121], v[2:3]
	v_mov_b64_e32 v[124:125], v[2:3]
	v_mov_b64_e32 v[128:129], v[2:3]
	v_mov_b64_e32 v[16:17], v[2:3]
	v_mov_b64_e32 v[12:13], v[2:3]
	v_mov_b64_e32 v[8:9], v[2:3]
	v_cmp_ne_u32_e64 s[0:1], 1, v4
	v_mov_b64_e32 v[18:19], v[0:1]
	v_mov_b64_e32 v[22:23], v[0:1]
	v_mov_b64_e32 v[26:27], v[0:1]
	v_mov_b64_e32 v[30:31], v[0:1]
	v_mov_b64_e32 v[34:35], v[0:1]
	v_mov_b64_e32 v[38:39], v[0:1]
	v_mov_b64_e32 v[42:43], v[0:1]
	v_mov_b64_e32 v[46:47], v[0:1]
	v_mov_b64_e32 v[50:51], v[0:1]
	v_mov_b64_e32 v[54:55], v[0:1]
	v_mov_b64_e32 v[58:59], v[0:1]
	v_mov_b64_e32 v[62:63], v[0:1]
	v_mov_b64_e32 v[66:67], v[0:1]
	v_mov_b64_e32 v[70:71], v[0:1]
	v_mov_b64_e32 v[74:75], v[0:1]
	v_mov_b64_e32 v[78:79], v[0:1]
	v_mov_b64_e32 v[82:83], v[0:1]
	v_mov_b64_e32 v[86:87], v[0:1]
	v_mov_b64_e32 v[90:91], v[0:1]
	v_mov_b64_e32 v[94:95], v[0:1]
	v_mov_b64_e32 v[98:99], v[0:1]
	v_mov_b64_e32 v[102:103], v[0:1]
	v_mov_b64_e32 v[106:107], v[0:1]
	v_mov_b64_e32 v[110:111], v[0:1]
	v_mov_b64_e32 v[114:115], v[0:1]
	v_mov_b64_e32 v[118:119], v[0:1]
	v_mov_b64_e32 v[122:123], v[0:1]
	v_mov_b64_e32 v[126:127], v[0:1]
	v_mov_b64_e32 v[14:15], v[0:1]
	v_mov_b64_e32 v[10:11], v[0:1]
	v_mov_b64_e32 v[6:7], v[0:1]
	v_mov_b64_e32 v[4:5], v[2:3]
	s_add_i32 s22, s11, -1
	s_lshl_b32 s23, s12, 12
	v_lshlrev_b32_e32 v168, 6, v167
	s_lshl_b32 s24, s13, 13
	s_mov_b32 s25, 0x18000
	v_mov_b64_e32 v[2:3], v[0:1]
	s_mov_b32 s26, s7
	s_branch .LBB0_2755

.LBB0_3086:
	s_and_b32 vcc_lo, s2, 7
	s_lshl_b32 vcc_lo, vcc_lo, 5
	s_lshr_b32 vcc_hi, s2, 3
	s_or_b32 vcc_lo, vcc_lo, vcc_hi
	s_cmpk_lt_i32 s2, 0x100
	s_cselect_b32 vcc_lo, vcc_lo, s2
	s_cmpk_lt_i32 s2, 0x100
	s_cselect_b64 s[10:11], -1, 0
	s_lshl_b32 s0, vcc_lo, 6
	s_and_b32 s0, s0, 0xffffff00
	s_lshl_b32 s1, vcc_lo, 8
	s_and_b32 s12, s1, 0x300
	s_add_i32 s1, s0, 0xffffc000
	s_cmpk_gt_i32 s2, 0xff
	s_cselect_b32 s21, 0x4000, s0
	s_cselect_b32 s0, s1, 0
	s_cselect_b32 s13, 8, 0x80
	s_ashr_i32 s1, s0, 31
	s_lshl_b64 s[0:1], s[0:1], 1
	s_add_u32 s22, s96, s0
	s_addc_u32 s23, s97, s1
	s_waitcnt vmcnt(1)
	v_mov_b32_e32 v10, v174
	s_add_u32 s0, s52, s0
	s_addc_u32 s1, s53, s1
	v_readfirstlane_b32 s6, v10
	s_ashr_i32 s24, s6, 6
	v_bfe_u32 v0, v10, 2, 4
	s_lshl_b32 s15, s24, 4
	v_or_b32_e32 v2, s21, v0
	s_add_i32 s25, s15, 0x80
	v_or_b32_e32 v0, s12, v0
	s_and_b32 s14, s24, 3
	v_add_u32_e32 v12, s15, v2
	v_add_u32_e32 v4, s25, v2
	v_mov_b64_e32 v[2:3], s[22:23]
	s_waitcnt vmcnt(0)
	v_add_u32_e32 v8, s15, v0
	v_mov_b64_e32 v[6:7], s[0:1]
	v_add_u32_e32 v0, s25, v0
	s_ashr_i32 s15, s6, 8
	v_bfe_u32 v166, v10, 4, 2
	v_mad_i64_i32 v[4:5], s[22:23], v4, s16, v[2:3]
	v_mad_i64_i32 v[8:9], s[0:1], v8, s16, v[6:7]
	v_mad_i64_i32 v[6:7], s[0:1], v0, s16, v[6:7]
	v_mad_i64_i32 v[2:3], s[0:1], v12, s16, v[2:3]
	s_cmp_lg_u32 s15, 1
	v_bitop3_b32 v11, v166, v10, 3 bitop3:0x78
	s_cselect_b64 s[0:1], -1, 0
	s_lshl_b32 s6, s24, 10
	v_lshlrev_b32_e32 v0, 4, v11
	s_add_i32 s22, s6, 0
	v_lshl_add_u64 v[158:159], v[2:3], 0, v[0:1]
	s_mov_b32 m0, s22
	v_lshl_add_u64 v[160:161], v[4:5], 0, v[0:1]
	global_load_lds_dwordx4 v[158:159], off
	s_add_i32 m0, s22, 0x2000
	v_lshl_add_u64 v[162:163], v[8:9], 0, v[0:1]
	global_load_lds_dwordx4 v[160:161], off
	s_add_i32 m0, s22, 0x4000
	v_lshl_add_u64 v[164:165], v[6:7], 0, v[0:1]
	global_load_lds_dwordx4 v[162:163], off
	s_add_i32 m0, s22, 0x6000
	v_lshl_add_u64 v[2:3], v[158:159], 0, 64
	global_load_lds_dwordx4 v[164:165], off
	s_add_i32 m0, s22, 0x8000
	s_add_i32 s23, s6, 0x2000
	global_load_lds_dwordx4 v[2:3], off
	v_lshl_add_u64 v[2:3], v[160:161], 0, 64
	s_add_i32 m0, s22, 0xa000
	v_lshrrev_b32_e32 v0, 2, v10
	global_load_lds_dwordx4 v[2:3], off
	v_lshl_add_u64 v[2:3], v[162:163], 0, 64
	s_add_i32 m0, s22, 0xc000
	v_bitop3_b32 v0, v166, v0, 3 bitop3:0x78
	global_load_lds_dwordx4 v[2:3], off
	v_lshl_add_u64 v[2:3], v[164:165], 0, 64
	s_add_i32 m0, s22, 0xe000
	s_or_b64 s[0:1], s[10:11], s[0:1]
	global_load_lds_dwordx4 v[2:3], off
	v_lshl_add_u64 v[2:3], v[158:159], 0, s[8:9]
	s_add_i32 m0, s18, s6
	v_and_b32_e32 v167, 15, v10
	global_load_lds_dwordx4 v[2:3], off
	v_lshl_add_u64 v[2:3], v[160:161], 0, s[8:9]
	s_add_i32 m0, s18, s23
	v_lshlrev_b32_e32 v169, 4, v0
	global_load_lds_dwordx4 v[2:3], off
	v_lshl_add_u64 v[2:3], v[162:163], 0, s[8:9]
	s_add_i32 m0, s19, s6
	v_mov_b32_e32 v0, v1
	global_load_lds_dwordx4 v[2:3], off
	v_lshl_add_u64 v[2:3], v[164:165], 0, s[8:9]
	s_add_i32 m0, s19, s23
	v_cndmask_b32_e64 v4, 0, 1, s[0:1]
	global_load_lds_dwordx4 v[2:3], off
	s_waitcnt vmcnt(8)
	v_mov_b32_e32 v2, v1
	v_mov_b32_e32 v3, v1
	s_waitcnt lgkmcnt(0)
	s_barrier
	v_mov_b64_e32 v[20:21], v[2:3]
	v_mov_b64_e32 v[24:25], v[2:3]
	v_mov_b64_e32 v[28:29], v[2:3]
	v_mov_b64_e32 v[32:33], v[2:3]
	v_mov_b64_e32 v[36:37], v[2:3]
	v_mov_b64_e32 v[40:41], v[2:3]
	v_mov_b64_e32 v[44:45], v[2:3]
	v_mov_b64_e32 v[48:49], v[2:3]
	v_mov_b64_e32 v[52:53], v[2:3]
	v_mov_b64_e32 v[56:57], v[2:3]
	v_mov_b64_e32 v[60:61], v[2:3]
	v_mov_b64_e32 v[64:65], v[2:3]
	v_mov_b64_e32 v[68:69], v[2:3]
	v_mov_b64_e32 v[72:73], v[2:3]
	v_mov_b64_e32 v[76:77], v[2:3]
	v_mov_b64_e32 v[80:81], v[2:3]
	v_mov_b64_e32 v[84:85], v[2:3]
	v_mov_b64_e32 v[88:89], v[2:3]
	v_mov_b64_e32 v[92:93], v[2:3]
	v_mov_b64_e32 v[96:97], v[2:3]
	v_mov_b64_e32 v[100:101], v[2:3]
	v_mov_b64_e32 v[104:105], v[2:3]
	v_mov_b64_e32 v[108:109], v[2:3]
	v_mov_b64_e32 v[112:113], v[2:3]
	v_mov_b64_e32 v[116:117], v[2:3]
	v_mov_b64_e32 v[120:121], v[2:3]
	v_mov_b64_e32 v[124:125], v[2:3]
	v_mov_b64_e32 v[128:129], v[2:3]
	v_mov_b64_e32 v[16:17], v[2:3]
	v_mov_b64_e32 v[12:13], v[2:3]
	v_mov_b64_e32 v[8:9], v[2:3]
	v_cmp_ne_u32_e64 s[0:1], 1, v4
	v_mov_b64_e32 v[18:19], v[0:1]
	v_mov_b64_e32 v[22:23], v[0:1]
	v_mov_b64_e32 v[26:27], v[0:1]
	v_mov_b64_e32 v[30:31], v[0:1]
	v_mov_b64_e32 v[34:35], v[0:1]
	v_mov_b64_e32 v[38:39], v[0:1]
	v_mov_b64_e32 v[42:43], v[0:1]
	v_mov_b64_e32 v[46:47], v[0:1]
	v_mov_b64_e32 v[50:51], v[0:1]
	v_mov_b64_e32 v[54:55], v[0:1]
	v_mov_b64_e32 v[58:59], v[0:1]
	v_mov_b64_e32 v[62:63], v[0:1]
	v_mov_b64_e32 v[66:67], v[0:1]
	v_mov_b64_e32 v[70:71], v[0:1]
	v_mov_b64_e32 v[74:75], v[0:1]
	v_mov_b64_e32 v[78:79], v[0:1]
	v_mov_b64_e32 v[82:83], v[0:1]
	v_mov_b64_e32 v[86:87], v[0:1]
	v_mov_b64_e32 v[90:91], v[0:1]
	v_mov_b64_e32 v[94:95], v[0:1]
	v_mov_b64_e32 v[98:99], v[0:1]
	v_mov_b64_e32 v[102:103], v[0:1]
	v_mov_b64_e32 v[106:107], v[0:1]
	v_mov_b64_e32 v[110:111], v[0:1]
	v_mov_b64_e32 v[114:115], v[0:1]
	v_mov_b64_e32 v[118:119], v[0:1]
	v_mov_b64_e32 v[122:123], v[0:1]
	v_mov_b64_e32 v[126:127], v[0:1]
	v_mov_b64_e32 v[14:15], v[0:1]
	v_mov_b64_e32 v[10:11], v[0:1]
	v_mov_b64_e32 v[6:7], v[0:1]
	v_mov_b64_e32 v[4:5], v[2:3]
	s_add_i32 s23, s13, -1
	s_lshl_b32 s24, s14, 12
	v_lshlrev_b32_e32 v168, 6, v167
	s_lshl_b32 s25, s15, 13
	s_mov_b32 s26, 0x18000
	v_mov_b64_e32 v[2:3], v[0:1]
	s_mov_b32 s27, s7
	s_branch .LBB0_3088
